# adds: PH10 ctx rows with batched slab loads (16 slabs), in-place residual epilogues PH9/PH16/PH19 in 3 load batches
# baseline (speedup 1.0000x reference)
;     __device__ __forceinline__ void operator()(const pg8::f32x4 (&acc)[2][2][4][2], const pg8::Unit& u, int wr, int wc, int fr, int fq) const {
;         const int R0 = u.pm * 256; const float* src; float* dst; int mv;
;         if (R0 < ML) { src = srcL + (size_t)R0 * D; dst = dstL + (size_t)R0 * D; mv = (R0 >= SEQ) ? 1 : 0; }
;         else { src = srcC + (size_t)(R0 - ML) * D; dst = dstC + (size_t)(R0 - ML) * D; mv = 2; }
;         const int col0 = u.pn * 256 + wc * 32 + 4 * fq; const float* gt = gate + mv * NMOD + col0;
;         pg8::f32x4 gv[2][2];
; #pragma unroll
;         for (int bj = 0; bj < 2; ++bj)
; #pragma unroll
;             for (int n = 0; n < 2; ++n) gv[bj][n] = *(const pg8::f32x4*)(gt + bj * 128 + n * 16);
; #pragma unroll
;         for (int ai = 0; ai < 2; ++ai)
; #pragma unroll
;             for (int m = 0; m < 4; ++m) { const size_t off = (size_t)(wr * 64 + fr + ai * 128 + m * 16) * D + col0;
; #pragma unroll
;                 for (int bj = 0; bj < 2; ++bj)
; #pragma unroll
;                     for (int n = 0; n < 2; ++n) { const pg8::f32x4 s = *(const pg8::f32x4*)(src + off + bj * 128 + n * 16);
;                         *(pg8::f32x4*)(dst + off + bj * 128 + n * 16) = s * ALPHA + gv[bj][n] * acc[ai][bj][m][n]; }
;                 asm volatile("" ::: "memory"); }
.LBB0_954:
	v_lshl_or_b32 v128, s64, 8, v185
	v_ashrrev_i32_e32 v129, 31, v128
	v_lshlrev_b64 v[172:173], 2, v[128:129]
	s_lshl_b32 s2, s78, 2
	s_add_u32 s64, s86, s2
	s_addc_u32 s65, s87, 0
	v_lshl_add_u64 v[128:129], s[64:65], 0, v[172:173]
	global_load_dwordx4 v[140:143], v[128:129], off
	global_load_dwordx4 v[136:139], v[128:129], off offset:64
	global_load_dwordx4 v[132:135], v[128:129], off offset:512
	s_nop 0
	global_load_dwordx4 v[128:131], v[128:129], off offset:576
	s_andn2_b64 vcc, exec, s[0:1]
	s_mov_b64 s[0:1], -1
	v_lshl_add_u64 v[234:235], s[62:63], 0, v[148:149]
	v_lshl_add_u64 v[234:235], v[234:235], 0, v[172:173]
	global_load_dwordx4 v[190:193], v[234:235], off
	global_load_dwordx4 v[194:197], v[234:235], off offset:64
	global_load_dwordx4 v[198:201], v[234:235], off offset:512
	global_load_dwordx4 v[202:205], v[234:235], off offset:576
	v_lshl_add_u64 v[234:235], s[62:63], 0, v[150:151]
	v_lshl_add_u64 v[234:235], v[234:235], 0, v[172:173]
	global_load_dwordx4 v[206:209], v[234:235], off
	global_load_dwordx4 v[210:213], v[234:235], off offset:64
	global_load_dwordx4 v[214:217], v[234:235], off offset:512
	global_load_dwordx4 v[218:221], v[234:235], off offset:576
	v_lshl_add_u64 v[236:237], s[62:63], 0, v[148:149]
	v_lshl_add_u64 v[236:237], v[236:237], 0, v[172:173]
	s_waitcnt vmcnt(7)
	v_pk_mul_f32 v[192:193], v[192:193], s[34:35] op_sel_hi:[1,0]
	v_pk_mul_f32 v[190:191], v[190:191], s[34:35] op_sel_hi:[1,0]
	v_pk_fma_f32 v[192:193], v[126:127], v[142:143], v[192:193]
	v_pk_fma_f32 v[190:191], v[124:125], v[140:141], v[190:191]
	global_store_dwordx4 v[236:237], v[190:193], off
	s_waitcnt vmcnt(7)
	v_pk_mul_f32 v[196:197], v[196:197], s[34:35] op_sel_hi:[1,0]
	v_pk_mul_f32 v[194:195], v[194:195], s[34:35] op_sel_hi:[1,0]
	v_pk_fma_f32 v[196:197], v[122:123], v[138:139], v[196:197]
	v_pk_fma_f32 v[194:195], v[120:121], v[136:137], v[194:195]
	global_store_dwordx4 v[236:237], v[194:197], off offset:64
	s_waitcnt vmcnt(7)
	v_pk_mul_f32 v[200:201], v[200:201], s[34:35] op_sel_hi:[1,0]
	v_pk_mul_f32 v[198:199], v[198:199], s[34:35] op_sel_hi:[1,0]
	v_pk_fma_f32 v[200:201], v[118:119], v[134:135], v[200:201]
	v_pk_fma_f32 v[198:199], v[116:117], v[132:133], v[198:199]
	global_store_dwordx4 v[236:237], v[198:201], off offset:512
	s_waitcnt vmcnt(7)
	v_pk_mul_f32 v[204:205], v[204:205], s[34:35] op_sel_hi:[1,0]
	v_pk_mul_f32 v[202:203], v[202:203], s[34:35] op_sel_hi:[1,0]
	v_pk_fma_f32 v[204:205], v[114:115], v[130:131], v[204:205]
	v_pk_fma_f32 v[202:203], v[112:113], v[128:129], v[202:203]
	global_store_dwordx4 v[236:237], v[202:205], off offset:576
	s_nop 1
	v_lshl_add_u64 v[236:237], s[62:63], 0, v[150:151]
	v_lshl_add_u64 v[236:237], v[236:237], 0, v[172:173]
	s_waitcnt vmcnt(7)
	v_pk_mul_f32 v[208:209], v[208:209], s[34:35] op_sel_hi:[1,0]
	v_pk_mul_f32 v[206:207], v[206:207], s[34:35] op_sel_hi:[1,0]
	v_pk_fma_f32 v[208:209], v[110:111], v[142:143], v[208:209]
	v_pk_fma_f32 v[206:207], v[108:109], v[140:141], v[206:207]
	global_store_dwordx4 v[236:237], v[206:209], off
	s_waitcnt vmcnt(7)
	v_pk_mul_f32 v[212:213], v[212:213], s[34:35] op_sel_hi:[1,0]
	v_pk_mul_f32 v[210:211], v[210:211], s[34:35] op_sel_hi:[1,0]
	v_pk_fma_f32 v[212:213], v[106:107], v[138:139], v[212:213]
	v_pk_fma_f32 v[210:211], v[104:105], v[136:137], v[210:211]
	global_store_dwordx4 v[236:237], v[210:213], off offset:64
	s_waitcnt vmcnt(7)
	v_pk_mul_f32 v[216:217], v[216:217], s[34:35] op_sel_hi:[1,0]
	v_pk_mul_f32 v[214:215], v[214:215], s[34:35] op_sel_hi:[1,0]
	v_pk_fma_f32 v[216:217], v[102:103], v[134:135], v[216:217]
	v_pk_fma_f32 v[214:215], v[100:101], v[132:133], v[214:215]
	global_store_dwordx4 v[236:237], v[214:217], off offset:512
	s_waitcnt vmcnt(7)
	v_pk_mul_f32 v[220:221], v[220:221], s[34:35] op_sel_hi:[1,0]
	v_pk_mul_f32 v[218:219], v[218:219], s[34:35] op_sel_hi:[1,0]
	v_pk_fma_f32 v[220:221], v[98:99], v[130:131], v[220:221]
	v_pk_fma_f32 v[218:219], v[96:97], v[128:129], v[218:219]
	global_store_dwordx4 v[236:237], v[218:221], off offset:576
	s_nop 1
	v_lshl_add_u64 v[234:235], s[62:63], 0, v[152:153]
	v_lshl_add_u64 v[234:235], v[234:235], 0, v[172:173]
	global_load_dwordx4 v[124:127], v[234:235], off
	global_load_dwordx4 v[120:123], v[234:235], off offset:64
	global_load_dwordx4 v[116:119], v[234:235], off offset:512
	global_load_dwordx4 v[112:115], v[234:235], off offset:576
	v_lshl_add_u64 v[234:235], s[62:63], 0, v[154:155]
	v_lshl_add_u64 v[234:235], v[234:235], 0, v[172:173]
	global_load_dwordx4 v[108:111], v[234:235], off
	global_load_dwordx4 v[104:107], v[234:235], off offset:64
	global_load_dwordx4 v[100:103], v[234:235], off offset:512
	global_load_dwordx4 v[96:99], v[234:235], off offset:576
	v_lshl_add_u64 v[234:235], s[62:63], 0, v[156:157]
	v_lshl_add_u64 v[234:235], v[234:235], 0, v[172:173]
	global_load_dwordx4 v[222:225], v[234:235], off
	global_load_dwordx4 v[226:229], v[234:235], off offset:64
	global_load_dwordx4 v[230:233], v[234:235], off offset:512
	global_load_dwordx4 v[190:193], v[234:235], off offset:576
	v_lshl_add_u64 v[236:237], s[62:63], 0, v[152:153]
	v_lshl_add_u64 v[236:237], v[236:237], 0, v[172:173]
	s_waitcnt vmcnt(11)
	v_pk_mul_f32 v[126:127], v[126:127], s[34:35] op_sel_hi:[1,0]
	v_pk_mul_f32 v[124:125], v[124:125], s[34:35] op_sel_hi:[1,0]
	v_pk_fma_f32 v[126:127], v[94:95], v[142:143], v[126:127]
	v_pk_fma_f32 v[124:125], v[92:93], v[140:141], v[124:125]
	global_store_dwordx4 v[236:237], v[124:127], off
	s_waitcnt vmcnt(11)
	v_pk_mul_f32 v[122:123], v[122:123], s[34:35] op_sel_hi:[1,0]
	v_pk_mul_f32 v[120:121], v[120:121], s[34:35] op_sel_hi:[1,0]
	v_pk_fma_f32 v[122:123], v[90:91], v[138:139], v[122:123]
	v_pk_fma_f32 v[120:121], v[88:89], v[136:137], v[120:121]
	global_store_dwordx4 v[236:237], v[120:123], off offset:64
	s_waitcnt vmcnt(11)
;     __device__ __forceinline__ void operator()(const pg8::f32x4 (&acc)[2][2][4][2], const pg8::Unit& u, int wr, int wc, int fr, int fq) const {
;     ...
;         for (int ai = 0; ai < 2; ++ai)
; #pragma unroll
;             for (int m = 0; m < 4; ++m) { const size_t off = (size_t)(wr * 64 + fr + ai * 128 + m * 16) * D + col0;
; #pragma unroll
;                 for (int bj = 0; bj < 2; ++bj)
; #pragma unroll
;                     for (int n = 0; n < 2; ++n) { const pg8::f32x4 s = *(const pg8::f32x4*)(src + off + bj * 128 + n * 16);
;                         *(pg8::f32x4*)(dst + off + bj * 128 + n * 16) = s * ALPHA + gv[bj][n] * acc[ai][bj][m][n]; }
;                 asm volatile("" ::: "memory"); }
	v_pk_mul_f32 v[118:119], v[118:119], s[34:35] op_sel_hi:[1,0]
	v_pk_mul_f32 v[116:117], v[116:117], s[34:35] op_sel_hi:[1,0]
	v_pk_fma_f32 v[118:119], v[86:87], v[134:135], v[118:119]
	v_pk_fma_f32 v[116:117], v[84:85], v[132:133], v[116:117]
	global_store_dwordx4 v[236:237], v[116:119], off offset:512
	s_waitcnt vmcnt(11)
	v_pk_mul_f32 v[114:115], v[114:115], s[34:35] op_sel_hi:[1,0]
	v_pk_mul_f32 v[112:113], v[112:113], s[34:35] op_sel_hi:[1,0]
	v_pk_fma_f32 v[114:115], v[82:83], v[130:131], v[114:115]
	v_pk_fma_f32 v[112:113], v[80:81], v[128:129], v[112:113]
	global_store_dwordx4 v[236:237], v[112:115], off offset:576
	s_nop 1
	v_lshl_add_u64 v[236:237], s[62:63], 0, v[154:155]
	v_lshl_add_u64 v[236:237], v[236:237], 0, v[172:173]
	s_waitcnt vmcnt(11)
	v_pk_mul_f32 v[110:111], v[110:111], s[34:35] op_sel_hi:[1,0]
	v_pk_mul_f32 v[108:109], v[108:109], s[34:35] op_sel_hi:[1,0]
	v_pk_fma_f32 v[110:111], v[78:79], v[142:143], v[110:111]
	v_pk_fma_f32 v[108:109], v[76:77], v[140:141], v[108:109]
	global_store_dwordx4 v[236:237], v[108:111], off
	s_waitcnt vmcnt(11)
	v_pk_mul_f32 v[106:107], v[106:107], s[34:35] op_sel_hi:[1,0]
	v_pk_mul_f32 v[104:105], v[104:105], s[34:35] op_sel_hi:[1,0]
	v_pk_fma_f32 v[106:107], v[74:75], v[138:139], v[106:107]
	v_pk_fma_f32 v[104:105], v[72:73], v[136:137], v[104:105]
	global_store_dwordx4 v[236:237], v[104:107], off offset:64
	s_waitcnt vmcnt(11)
	v_pk_mul_f32 v[102:103], v[102:103], s[34:35] op_sel_hi:[1,0]
	v_pk_mul_f32 v[100:101], v[100:101], s[34:35] op_sel_hi:[1,0]
	v_pk_fma_f32 v[102:103], v[70:71], v[134:135], v[102:103]
	v_pk_fma_f32 v[100:101], v[68:69], v[132:133], v[100:101]
	global_store_dwordx4 v[236:237], v[100:103], off offset:512
	s_waitcnt vmcnt(11)
	v_pk_mul_f32 v[98:99], v[98:99], s[34:35] op_sel_hi:[1,0]
	v_pk_mul_f32 v[96:97], v[96:97], s[34:35] op_sel_hi:[1,0]
	v_pk_fma_f32 v[98:99], v[66:67], v[130:131], v[98:99]
	v_pk_fma_f32 v[96:97], v[64:65], v[128:129], v[96:97]
	global_store_dwordx4 v[236:237], v[96:99], off offset:576
	s_nop 1
	v_lshl_add_u64 v[236:237], s[62:63], 0, v[156:157]
	v_lshl_add_u64 v[236:237], v[236:237], 0, v[172:173]
	s_waitcnt vmcnt(11)
	v_pk_mul_f32 v[224:225], v[224:225], s[34:35] op_sel_hi:[1,0]
	v_pk_mul_f32 v[222:223], v[222:223], s[34:35] op_sel_hi:[1,0]
	v_pk_fma_f32 v[224:225], v[62:63], v[142:143], v[224:225]
	v_pk_fma_f32 v[222:223], v[60:61], v[140:141], v[222:223]
	global_store_dwordx4 v[236:237], v[222:225], off
	s_waitcnt vmcnt(11)
	v_pk_mul_f32 v[228:229], v[228:229], s[34:35] op_sel_hi:[1,0]
	v_pk_mul_f32 v[226:227], v[226:227], s[34:35] op_sel_hi:[1,0]
	v_pk_fma_f32 v[228:229], v[58:59], v[138:139], v[228:229]
	v_pk_fma_f32 v[226:227], v[56:57], v[136:137], v[226:227]
	global_store_dwordx4 v[236:237], v[226:229], off offset:64
	s_waitcnt vmcnt(11)
	v_pk_mul_f32 v[232:233], v[232:233], s[34:35] op_sel_hi:[1,0]
	v_pk_mul_f32 v[230:231], v[230:231], s[34:35] op_sel_hi:[1,0]
	v_pk_fma_f32 v[232:233], v[54:55], v[134:135], v[232:233]
	v_pk_fma_f32 v[230:231], v[52:53], v[132:133], v[230:231]
	global_store_dwordx4 v[236:237], v[230:233], off offset:512
	s_waitcnt vmcnt(11)
	v_pk_mul_f32 v[192:193], v[192:193], s[34:35] op_sel_hi:[1,0]
	v_pk_mul_f32 v[190:191], v[190:191], s[34:35] op_sel_hi:[1,0]
	v_pk_fma_f32 v[192:193], v[50:51], v[130:131], v[192:193]
	v_pk_fma_f32 v[190:191], v[48:49], v[128:129], v[190:191]
	global_store_dwordx4 v[236:237], v[190:193], off offset:576
	s_nop 1
	v_lshl_add_u64 v[234:235], s[62:63], 0, v[158:159]
	v_lshl_add_u64 v[234:235], v[234:235], 0, v[172:173]
	global_load_dwordx4 v[194:197], v[234:235], off
	global_load_dwordx4 v[198:201], v[234:235], off offset:64
	global_load_dwordx4 v[202:205], v[234:235], off offset:512
	global_load_dwordx4 v[206:209], v[234:235], off offset:576
	v_lshl_add_u64 v[234:235], s[62:63], 0, v[160:161]
	v_lshl_add_u64 v[234:235], v[234:235], 0, v[172:173]
	global_load_dwordx4 v[210:213], v[234:235], off
	global_load_dwordx4 v[214:217], v[234:235], off offset:64
	global_load_dwordx4 v[218:221], v[234:235], off offset:512
	global_load_dwordx4 v[92:95], v[234:235], off offset:576
	v_lshl_add_u64 v[234:235], s[62:63], 0, v[162:163]
	v_lshl_add_u64 v[234:235], v[234:235], 0, v[172:173]
	global_load_dwordx4 v[88:91], v[234:235], off
	global_load_dwordx4 v[84:87], v[234:235], off offset:64
	global_load_dwordx4 v[80:83], v[234:235], off offset:512
	global_load_dwordx4 v[76:79], v[234:235], off offset:576
	v_lshl_add_u64 v[236:237], s[62:63], 0, v[158:159]
	v_lshl_add_u64 v[236:237], v[236:237], 0, v[172:173]
	s_waitcnt vmcnt(11)
; template <class Epi, class Sched, bool ALIGN_EPI = false, bool SP2 = false>
; __device__ __forceinline__ void gemm_phase(PG8_LAS unsigned char* lds, const Gemm g, const Sched& S, const Epi& E) {
;     ...
;         if constexpr (!Epi::AFTER_DRAIN) { E(acc, cur, wr, wc, fr, fq); S.done(cur); }
;     __device__ __forceinline__ void operator()(const pg8::f32x4 (&acc)[2][2][4][2], const pg8::Unit& u, int wr, int wc, int fr, int fq) const {
;     ...
;         for (int ai = 0; ai < 2; ++ai)
; #pragma unroll
;             for (int m = 0; m < 4; ++m) { const size_t off = (size_t)(wr * 64 + fr + ai * 128 + m * 16) * D + col0;
; #pragma unroll
;                 for (int bj = 0; bj < 2; ++bj)
; #pragma unroll
;                     for (int n = 0; n < 2; ++n) { const pg8::f32x4 s = *(const pg8::f32x4*)(src + off + bj * 128 + n * 16);
;                         *(pg8::f32x4*)(dst + off + bj * 128 + n * 16) = s * ALPHA + gv[bj][n] * acc[ai][bj][m][n]; }
;                 asm volatile("" ::: "memory"); }
	v_pk_mul_f32 v[196:197], v[196:197], s[34:35] op_sel_hi:[1,0]
	v_pk_mul_f32 v[194:195], v[194:195], s[34:35] op_sel_hi:[1,0]
	v_pk_fma_f32 v[196:197], v[46:47], v[142:143], v[196:197]
	v_pk_fma_f32 v[194:195], v[44:45], v[140:141], v[194:195]
	global_store_dwordx4 v[236:237], v[194:197], off
	s_waitcnt vmcnt(11)
	v_pk_mul_f32 v[200:201], v[200:201], s[34:35] op_sel_hi:[1,0]
	v_pk_mul_f32 v[198:199], v[198:199], s[34:35] op_sel_hi:[1,0]
	v_pk_fma_f32 v[200:201], v[42:43], v[138:139], v[200:201]
	v_pk_fma_f32 v[198:199], v[40:41], v[136:137], v[198:199]
	global_store_dwordx4 v[236:237], v[198:201], off offset:64
	s_waitcnt vmcnt(11)
	v_pk_mul_f32 v[204:205], v[204:205], s[34:35] op_sel_hi:[1,0]
	v_pk_mul_f32 v[202:203], v[202:203], s[34:35] op_sel_hi:[1,0]
	v_pk_fma_f32 v[204:205], v[38:39], v[134:135], v[204:205]
	v_pk_fma_f32 v[202:203], v[36:37], v[132:133], v[202:203]
	global_store_dwordx4 v[236:237], v[202:205], off offset:512
	s_waitcnt vmcnt(11)
	v_pk_mul_f32 v[208:209], v[208:209], s[34:35] op_sel_hi:[1,0]
	v_pk_mul_f32 v[206:207], v[206:207], s[34:35] op_sel_hi:[1,0]
	v_pk_fma_f32 v[208:209], v[34:35], v[130:131], v[208:209]
	v_pk_fma_f32 v[206:207], v[32:33], v[128:129], v[206:207]
	global_store_dwordx4 v[236:237], v[206:209], off offset:576
	s_nop 1
	v_lshl_add_u64 v[236:237], s[62:63], 0, v[160:161]
	v_lshl_add_u64 v[236:237], v[236:237], 0, v[172:173]
	s_waitcnt vmcnt(11)
	v_pk_mul_f32 v[212:213], v[212:213], s[34:35] op_sel_hi:[1,0]
	v_pk_mul_f32 v[210:211], v[210:211], s[34:35] op_sel_hi:[1,0]
	v_pk_fma_f32 v[212:213], v[30:31], v[142:143], v[212:213]
	v_pk_fma_f32 v[210:211], v[28:29], v[140:141], v[210:211]
	global_store_dwordx4 v[236:237], v[210:213], off
	s_waitcnt vmcnt(11)
	v_pk_mul_f32 v[216:217], v[216:217], s[34:35] op_sel_hi:[1,0]
	v_pk_mul_f32 v[214:215], v[214:215], s[34:35] op_sel_hi:[1,0]
	v_pk_fma_f32 v[216:217], v[26:27], v[138:139], v[216:217]
	v_pk_fma_f32 v[214:215], v[24:25], v[136:137], v[214:215]
	global_store_dwordx4 v[236:237], v[214:217], off offset:64
	s_waitcnt vmcnt(11)
	v_pk_mul_f32 v[220:221], v[220:221], s[34:35] op_sel_hi:[1,0]
	v_pk_mul_f32 v[218:219], v[218:219], s[34:35] op_sel_hi:[1,0]
	v_pk_fma_f32 v[220:221], v[22:23], v[134:135], v[220:221]
	v_pk_fma_f32 v[218:219], v[20:21], v[132:133], v[218:219]
	global_store_dwordx4 v[236:237], v[218:221], off offset:512
	s_waitcnt vmcnt(11)
	v_pk_mul_f32 v[94:95], v[94:95], s[34:35] op_sel_hi:[1,0]
	v_pk_mul_f32 v[92:93], v[92:93], s[34:35] op_sel_hi:[1,0]
	v_pk_fma_f32 v[94:95], v[18:19], v[130:131], v[94:95]
	v_pk_fma_f32 v[92:93], v[16:17], v[128:129], v[92:93]
	global_store_dwordx4 v[236:237], v[92:95], off offset:576
	s_nop 1
	v_lshl_add_u64 v[236:237], s[62:63], 0, v[162:163]
	v_lshl_add_u64 v[236:237], v[236:237], 0, v[172:173]
	s_waitcnt vmcnt(11)
	v_pk_mul_f32 v[90:91], v[90:91], s[34:35] op_sel_hi:[1,0]
	v_pk_mul_f32 v[88:89], v[88:89], s[34:35] op_sel_hi:[1,0]
	v_pk_fma_f32 v[90:91], v[14:15], v[142:143], v[90:91]
	v_pk_fma_f32 v[88:89], v[12:13], v[140:141], v[88:89]
	global_store_dwordx4 v[236:237], v[88:91], off
	s_waitcnt vmcnt(11)
	v_pk_mul_f32 v[86:87], v[86:87], s[34:35] op_sel_hi:[1,0]
	v_pk_mul_f32 v[84:85], v[84:85], s[34:35] op_sel_hi:[1,0]
	v_pk_fma_f32 v[86:87], v[10:11], v[138:139], v[86:87]
	v_pk_fma_f32 v[84:85], v[8:9], v[136:137], v[84:85]
	global_store_dwordx4 v[236:237], v[84:87], off offset:64
	s_waitcnt vmcnt(11)
	v_pk_mul_f32 v[82:83], v[82:83], s[34:35] op_sel_hi:[1,0]
	v_pk_mul_f32 v[80:81], v[80:81], s[34:35] op_sel_hi:[1,0]
	v_pk_fma_f32 v[82:83], v[6:7], v[134:135], v[82:83]
	v_pk_fma_f32 v[80:81], v[4:5], v[132:133], v[80:81]
	global_store_dwordx4 v[236:237], v[80:83], off offset:512
	s_waitcnt vmcnt(11)
	v_pk_mul_f32 v[78:79], v[78:79], s[34:35] op_sel_hi:[1,0]
	v_pk_mul_f32 v[76:77], v[76:77], s[34:35] op_sel_hi:[1,0]
	v_pk_fma_f32 v[78:79], v[2:3], v[130:131], v[78:79]
	v_pk_fma_f32 v[76:77], v[0:1], v[128:129], v[76:77]
	global_store_dwordx4 v[236:237], v[76:79], off offset:576
	s_nop 1
	s_cbranch_vccnz .LBB0_939
	s_andn2_b64 vcc, exec, s[8:9]
	s_cbranch_vccnz .LBB0_938
	s_barrier
	s_branch .LBB0_938

;     f32x4 nv[8];
;     if (gw < nrows) { const float* s0_ = (gw < ML) ? srcL + (size_t)gw * D : srcC + (size_t)(gw - ML) * D;
; #pragma unroll
;         for (int j = 0; j < 8; ++j) nv[j] = *(const f32x4*)(s0_ + lane * 4 + 256 * j); }
;     for (int m = gw; m < nrows; m += NGW) {
;         float* dst; int mv;
;         if (m < ML) { dst = dstL + (size_t)m * D; mv = (m >= SEQ) ? 1 : 0; }
;         else { dst = dstC + (size_t)(m - ML) * D; mv = 2; }
;         f32x4 v[8];
; #pragma unroll
;         for (int j = 0; j < 8; ++j) v[j] = nv[j];
;         { const int mn = m + NGW;
;           if (mn < nrows) { const float* s1_ = (mn < ML) ? srcL + (size_t)mn * D : srcC + (size_t)(mn - ML) * D;
; #pragma unroll
;               for (int j = 0; j < 8; ++j) nv[j] = *(const f32x4*)(s1_ + lane * 4 + 256 * j); } }
.LBB0_1028:
	s_cmp_lt_i32 s72, 11
	s_cselect_b64 s[0:1], -1, 0
	s_cmp_gt_i32 s73, 10
	s_cselect_b64 s[4:5], -1, 0
	s_and_b64 s[0:1], s[0:1], s[4:5]
	s_andn2_b64 vcc, exec, s[0:1]
	s_cbranch_vccnz .LBB0_1123
	v_readfirstlane_b32 s0, v174
	s_lshr_b32 s7, s0, 6
	v_readlane_b32 s0, v246, 0
	s_lshl_b32 s0, s0, 3
	s_add_i32 s3, s7, s0
	s_lshl_b32 s6, s74, 3
	s_cmpk_gt_i32 s3, 0x3fff
	s_waitcnt vmcnt(0)
	v_and_b32_e32 v71, 63, v174
	s_cbranch_scc1 .LBB0_1041
	s_add_u32 s9, s70, 0x6300000
	s_addc_u32 s28, s71, 0
	s_add_u32 s29, s70, 0x24000
	s_addc_u32 s33, s71, 0
	s_add_i32 s0, s3, 0xffffc000
	s_ashr_i32 s1, s3, 31
	s_cmpk_lt_i32 s3, 0x4000
	s_cselect_b32 s5, s1, 0
	s_cselect_b32 s4, s3, s0
	s_cselect_b32 s1, s69, s28
	s_cselect_b32 s2, s68, s9
	s_lshl_b64 s[4:5], s[4:5], 13
	s_add_u32 s4, s2, s4
	s_addc_u32 s5, s1, s5
	v_mov_b32_e32 v69, 0
	v_lshlrev_b32_e32 v68, 4, v71
	v_lshl_add_u64 v[0:1], s[4:5], 0, v[68:69]
	s_movk_i32 s58, 0x1000
	v_add_co_u32_e32 v0, vcc, s58, v0
	global_load_dwordx4 v[60:63], v68, s[4:5]
	global_load_dwordx4 v[56:59], v68, s[4:5] offset:1024
	global_load_dwordx4 v[52:55], v68, s[4:5] offset:2048
	global_load_dwordx4 v[48:51], v68, s[4:5] offset:3072
	v_addc_co_u32_e32 v1, vcc, 0, v1, vcc
	global_load_dwordx4 v[44:47], v[0:1], off
	global_load_dwordx4 v[40:43], v[0:1], off offset:1024
	global_load_dwordx4 v[36:39], v[0:1], off offset:2048
	global_load_dwordx4 v[32:35], v[0:1], off offset:3072
	v_lshlrev_b32_e32 v0, 3, v71
	v_mov_b32_e32 v1, v69
	v_lshl_add_u64 v[0:1], s[70:71], 0, v[0:1]
	s_mov_b64 s[10:11], 0x6700000
	v_lshl_add_u64 v[76:77], v[0:1], 0, s[10:11]
	v_mbcnt_lo_u32_b32 v0, -1, 0
	v_mbcnt_hi_u32_b32 v0, -1, v0
	v_and_b32_e32 v1, 64, v0
	v_add_u32_e32 v1, 64, v1
	v_xor_b32_e32 v2, 1, v0
	v_cmp_lt_i32_e32 vcc, v2, v1
	v_readlane_b32 s60, v246, 1
	v_readlane_b32 s64, v246, 5
	v_cndmask_b32_e32 v2, v0, v2, vcc
	v_lshlrev_b32_e32 v98, 2, v2
	v_xor_b32_e32 v2, 2, v0
	v_cmp_lt_i32_e32 vcc, v2, v1
	v_readlane_b32 s65, v246, 6
	v_readlane_b32 s66, v246, 7
	v_cndmask_b32_e32 v2, v0, v2, vcc
	v_lshlrev_b32_e32 v99, 2, v2
	v_xor_b32_e32 v2, 4, v0
	v_cmp_lt_i32_e32 vcc, v2, v1
	v_readlane_b32 s67, v246, 8
	v_lshl_add_u64 v[72:73], s[64:65], 0, v[68:69]
	v_cndmask_b32_e32 v2, v0, v2, vcc
	v_lshlrev_b32_e32 v100, 2, v2
	v_xor_b32_e32 v2, 8, v0
	v_cmp_lt_i32_e32 vcc, v2, v1
	v_lshl_add_u64 v[74:75], s[66:67], 0, v[68:69]
	s_mov_b64 s[10:11], 0x1000
	v_cndmask_b32_e32 v2, v0, v2, vcc
	v_lshlrev_b32_e32 v101, 2, v2
	v_xor_b32_e32 v2, 16, v0
	v_cmp_lt_i32_e32 vcc, v2, v1
	v_lshl_add_u64 v[78:79], v[72:73], 0, s[10:11]
	v_lshl_add_u64 v[80:81], v[74:75], 0, s[10:11]
	v_cndmask_b32_e32 v2, v0, v2, vcc
	s_mov_b64 s[10:11], 0x1400
	v_lshlrev_b32_e32 v102, 2, v2
	v_xor_b32_e32 v2, 32, v0
	v_lshl_add_u64 v[82:83], v[72:73], 0, s[10:11]
	v_lshl_add_u64 v[84:85], v[74:75], 0, s[10:11]
	s_mov_b64 s[10:11], 0x1800
	v_cmp_lt_i32_e32 vcc, v2, v1
	v_readlane_b32 s61, v246, 2
	v_readlane_b32 s62, v246, 3
	v_readlane_b32 s63, v246, 4
	v_lshl_add_u64 v[86:87], v[72:73], 0, s[10:11]
	v_lshl_add_u64 v[88:89], v[74:75], 0, s[10:11]
	s_mov_b64 s[10:11], 0x1c00
	v_cndmask_b32_e32 v0, v0, v2, vcc
	s_mov_b32 s5, 0
	v_lshlrev_b32_e32 v70, 2, v71
	v_lshl_add_u64 v[90:91], v[72:73], 0, s[10:11]
	v_lshl_add_u64 v[92:93], v[74:75], 0, s[10:11]
	v_lshlrev_b32_e32 v103, 2, v0
	v_lshl_add_u64 v[94:95], s[70:71], 0, v[68:69]
	s_movk_i32 s59, 0x3000
	s_mov_b32 s8, 0x3fb504f3
	s_mov_b32 s60, 0x1b800000
	s_mov_b32 s61, 0x1b801000
	s_mov_b32 s62, 0x1bc00000
	s_mov_b32 s63, 0x1bc01000
	s_brev_b32 s64, 56
	s_mov_b32 s65, 0x1c001000
	s_mov_b32 s66, 0x1c400000
	s_mov_b32 s67, 0x1c401000
	v_mov_b32_e32 v104, 0x3727c5ac
	s_mov_b32 s76, 0x800000
	s_mov_b64 s[10:11], 0x2000
	s_movk_i32 s77, 0x7fff
	s_mov_b32 s78, 0xffff0000
	s_mov_b32 s34, s3
	s_branch .LBB0_1032

;     ...
;     for (int m = gw; m < nrows; m += NGW) {
;         float* dst; int mv;
;         if (m < ML) { dst = dstL + (size_t)m * D; mv = (m >= SEQ) ? 1 : 0; }
;         else { dst = dstC + (size_t)(m - ML) * D; mv = 2; }
;         f32x4 v[8];
; #pragma unroll
;         for (int j = 0; j < 8; ++j) v[j] = nv[j];
;         { const int mn = m + NGW;
;           if (mn < nrows) { const float* s1_ = (mn < ML) ? srcL + (size_t)mn * D : srcC + (size_t)(mn - ML) * D;
; #pragma unroll
;               for (int j = 0; j < 8; ++j) nv[j] = *(const f32x4*)(s1_ + lane * 4 + 256 * j); } }
.LBB0_1036:
	s_add_i32 s4, s34, s6
	s_cmpk_gt_i32 s4, 0x3fff
	s_cselect_b64 s[30:31], -1, 0
	s_waitcnt vmcnt(0)
	v_mov_b64_e32 v[28:29], v[32:33]
	v_mov_b64_e32 v[24:25], v[36:37]
	v_mov_b64_e32 v[20:21], v[40:41]
	v_mov_b64_e32 v[16:17], v[44:45]
	v_mov_b64_e32 v[12:13], v[48:49]
	v_mov_b64_e32 v[8:9], v[52:53]
	v_mov_b64_e32 v[4:5], v[56:57]
	v_mov_b64_e32 v[0:1], v[60:61]
	s_and_b64 vcc, exec, s[30:31]
	v_lshlrev_b32_e32 v68, 2, v70
	v_mov_b64_e32 v[30:31], v[34:35]
	v_mov_b64_e32 v[26:27], v[38:39]
	v_mov_b64_e32 v[22:23], v[42:43]
	v_mov_b64_e32 v[18:19], v[46:47]
	v_mov_b64_e32 v[14:15], v[50:51]
	v_mov_b64_e32 v[10:11], v[54:55]
	v_mov_b64_e32 v[6:7], v[58:59]
	v_mov_b64_e32 v[2:3], v[62:63]
	s_cbranch_vccnz .LBB0_1038
	s_add_i32 s1, s4, 0xffffc000
	s_ashr_i32 s2, s4, 31
	s_cmpk_lt_i32 s4, 0x4000
	s_cselect_b32 s57, s2, 0
	s_cselect_b32 s56, s4, s1
	s_cselect_b32 s1, s69, s28
	s_cselect_b32 s2, s68, s9
	s_lshl_b64 s[56:57], s[56:57], 13
	s_add_u32 s56, s2, s56
	s_addc_u32 s57, s1, s57
	v_lshl_add_u64 v[16:17], s[56:57], 0, v[68:69]
	v_add_co_u32_e32 v28, vcc, 0x1000, v16
	global_load_dwordx4 v[0:3], v68, s[56:57]
	global_load_dwordx4 v[4:7], v68, s[56:57] offset:1024
	global_load_dwordx4 v[8:11], v68, s[56:57] offset:2048
	global_load_dwordx4 v[12:15], v68, s[56:57] offset:3072
	v_addc_co_u32_e32 v29, vcc, 0, v17, vcc
	global_load_dwordx4 v[16:19], v[28:29], off
	global_load_dwordx4 v[20:23], v[28:29], off offset:1024
	global_load_dwordx4 v[24:27], v[28:29], off offset:2048
	s_nop 0
	global_load_dwordx4 v[28:31], v[28:29], off offset:3072

;     ...
;     if (gw < nrows) { const float* s0_ = (gw < ML) ? srcL + (size_t)gw * D : srcC + (size_t)(gw - ML) * D;
; #pragma unroll
;         for (int j = 0; j < 8; ++j) nv[j] = *(const f32x4*)(s0_ + lane * 4 + 256 * j); }
;     for (int m = gw; m < nrows; m += NGW) {
;         float* dst; int mv;
;         if (m < ML) { dst = dstL + (size_t)m * D; mv = (m >= SEQ) ? 1 : 0; }
;         else { dst = dstC + (size_t)(m - ML) * D; mv = 2; }
;         f32x4 v[8];
; #pragma unroll
;         for (int j = 0; j < 8; ++j) v[j] = nv[j];
;         { const int mn = m + NGW;
;           if (mn < nrows) { const float* s1_ = (mn < ML) ? srcL + (size_t)mn * D : srcC + (size_t)(mn - ML) * D;
; #pragma unroll
;               for (int j = 0; j < 8; ++j) nv[j] = *(const f32x4*)(s1_ + lane * 4 + 256 * j); } }
;         if (nslab > 0 && m >= ML) {
; #pragma unroll
;             for (int j = 0; j < 8; ++j) v[j] = v[j] * ALPHA;
;             for (int sidx = 0; sidx < nslab; ++sidx) { const float* sp = slab + ((size_t)sidx * (2 * CTXL) + (m - ML)) * D + lane * 4;
; #pragma unroll
;                 for (int j = 0; j < 8; ++j) v[j] += *(const f32x4*)(sp + 256 * j); }
.LBB0_1041:
	v_readfirstlane_b32 s60, v174
	v_readlane_b32 s61, v246, 0
	s_nop 3
	s_lshr_b32 s60, s60, 6
	s_lshl_b32 s61, s61, 3
	s_add_i32 s60, s60, s61
	s_cmpk_lt_i32 s60, 0x200
	s_cbranch_scc0 .Lcx10_done
	v_readlane_b32 s64, v246, 33
	v_readlane_b32 s65, v246, 34
	v_readlane_b32 s66, v246, 5
	v_readlane_b32 s67, v246, 6
	v_readlane_b32 s78, v246, 7
	v_readlane_b32 s79, v246, 8
	v_and_b32_e32 v240, 63, v174
	v_lshlrev_b32_e32 v241, 3, v240
	v_lshlrev_b32_e32 v240, 4, v240
	v_mov_b32_e32 v64, 0x3fb504f3
	s_nop 4
	s_lshl_b32 s58, s60, 13
	s_add_u32 s62, s64, 0x6300000
	s_addc_u32 s63, s65, 0
	s_add_u32 s18, s62, s58
	s_addc_u32 s19, s63, 0
	s_add_u32 s20, s18, 0x1000
	s_addc_u32 s21, s19, 0
	global_load_dwordx4 v[0:3], v240, s[18:19]
	global_load_dwordx4 v[4:7], v240, s[18:19] offset:1024
	global_load_dwordx4 v[8:11], v240, s[18:19] offset:2048
	global_load_dwordx4 v[12:15], v240, s[18:19] offset:3072
	global_load_dwordx4 v[16:19], v240, s[20:21]
	global_load_dwordx4 v[20:23], v240, s[20:21] offset:1024
	global_load_dwordx4 v[24:27], v240, s[20:21] offset:2048
	global_load_dwordx4 v[28:31], v240, s[20:21] offset:3072
	s_add_u32 s80, s66, 0x1000
	s_addc_u32 s81, s67, 0
	s_add_u32 s82, s78, 0x1000
	s_addc_u32 s83, s79, 0
	global_load_dwordx4 v[96:99], v240, s[66:67]
	global_load_dwordx4 v[100:103], v240, s[66:67] offset:1024
	global_load_dwordx4 v[104:107], v240, s[66:67] offset:2048
	global_load_dwordx4 v[108:111], v240, s[66:67] offset:3072
	global_load_dwordx4 v[112:115], v240, s[80:81]
	global_load_dwordx4 v[116:119], v240, s[80:81] offset:1024
	global_load_dwordx4 v[120:123], v240, s[80:81] offset:2048
	global_load_dwordx4 v[124:127], v240, s[80:81] offset:3072
	global_load_dwordx4 v[128:131], v240, s[78:79]
	global_load_dwordx4 v[132:135], v240, s[78:79] offset:1024
	global_load_dwordx4 v[136:139], v240, s[78:79] offset:2048
	global_load_dwordx4 v[140:143], v240, s[78:79] offset:3072
	global_load_dwordx4 v[144:147], v240, s[82:83]
	global_load_dwordx4 v[148:151], v240, s[82:83] offset:1024
	global_load_dwordx4 v[152:155], v240, s[82:83] offset:2048
	global_load_dwordx4 v[156:159], v240, s[82:83] offset:3072
	s_add_u32 s22, s64, 0x1b800000
	s_addc_u32 s23, s65, 0
	s_add_u32 s22, s22, s58
	s_addc_u32 s23, s23, 0
	s_add_u32 s24, s22, 0x0
	s_addc_u32 s25, s23, 0
	s_add_u32 s26, s24, 0x1000
	s_addc_u32 s27, s25, 0
	global_load_dwordx4 v[176:179], v240, s[24:25]
	global_load_dwordx4 v[180:183], v240, s[24:25] offset:1024
	global_load_dwordx4 v[184:187], v240, s[24:25] offset:2048
	global_load_dwordx4 v[188:191], v240, s[24:25] offset:3072
	global_load_dwordx4 v[192:195], v240, s[26:27]
	global_load_dwordx4 v[196:199], v240, s[26:27] offset:1024
	global_load_dwordx4 v[200:203], v240, s[26:27] offset:2048
	global_load_dwordx4 v[204:207], v240, s[26:27] offset:3072
	s_add_u32 s28, s22, 0x400000
	s_addc_u32 s29, s23, 0
	s_add_u32 s30, s28, 0x1000
	s_addc_u32 s31, s29, 0
	global_load_dwordx4 v[208:211], v240, s[28:29]
	global_load_dwordx4 v[212:215], v240, s[28:29] offset:1024
	global_load_dwordx4 v[216:219], v240, s[28:29] offset:2048
	global_load_dwordx4 v[220:223], v240, s[28:29] offset:3072
	global_load_dwordx4 v[224:227], v240, s[30:31]
	global_load_dwordx4 v[228:231], v240, s[30:31] offset:1024
	global_load_dwordx4 v[232:235], v240, s[30:31] offset:2048
	global_load_dwordx4 v[236:239], v240, s[30:31] offset:3072
	s_waitcnt vmcnt(15)
	v_pk_fma_f32 v[0:1], v[0:1], v[64:65], v[176:177] op_sel_hi:[1,0,1]
	v_pk_fma_f32 v[2:3], v[2:3], v[64:65], v[178:179] op_sel_hi:[1,0,1]
	s_waitcnt vmcnt(14)
	v_pk_fma_f32 v[4:5], v[4:5], v[64:65], v[180:181] op_sel_hi:[1,0,1]
	v_pk_fma_f32 v[6:7], v[6:7], v[64:65], v[182:183] op_sel_hi:[1,0,1]
	s_waitcnt vmcnt(13)
	v_pk_fma_f32 v[8:9], v[8:9], v[64:65], v[184:185] op_sel_hi:[1,0,1]
	v_pk_fma_f32 v[10:11], v[10:11], v[64:65], v[186:187] op_sel_hi:[1,0,1]
	s_waitcnt vmcnt(12)
	v_pk_fma_f32 v[12:13], v[12:13], v[64:65], v[188:189] op_sel_hi:[1,0,1]
	v_pk_fma_f32 v[14:15], v[14:15], v[64:65], v[190:191] op_sel_hi:[1,0,1]
	s_waitcnt vmcnt(11)
	v_pk_fma_f32 v[16:17], v[16:17], v[64:65], v[192:193] op_sel_hi:[1,0,1]
	v_pk_fma_f32 v[18:19], v[18:19], v[64:65], v[194:195] op_sel_hi:[1,0,1]
	s_waitcnt vmcnt(10)
	v_pk_fma_f32 v[20:21], v[20:21], v[64:65], v[196:197] op_sel_hi:[1,0,1]
	v_pk_fma_f32 v[22:23], v[22:23], v[64:65], v[198:199] op_sel_hi:[1,0,1]
	s_waitcnt vmcnt(9)
	v_pk_fma_f32 v[24:25], v[24:25], v[64:65], v[200:201] op_sel_hi:[1,0,1]
	v_pk_fma_f32 v[26:27], v[26:27], v[64:65], v[202:203] op_sel_hi:[1,0,1]
	s_waitcnt vmcnt(8)
	v_pk_fma_f32 v[28:29], v[28:29], v[64:65], v[204:205] op_sel_hi:[1,0,1]
	v_pk_fma_f32 v[30:31], v[30:31], v[64:65], v[206:207] op_sel_hi:[1,0,1]
	s_waitcnt vmcnt(7)
	v_pk_add_f32 v[0:1], v[0:1], v[208:209]
	v_pk_add_f32 v[2:3], v[2:3], v[210:211]
	s_waitcnt vmcnt(6)
	v_pk_add_f32 v[4:5], v[4:5], v[212:213]
	v_pk_add_f32 v[6:7], v[6:7], v[214:215]
	s_waitcnt vmcnt(5)
	v_pk_add_f32 v[8:9], v[8:9], v[216:217]
	v_pk_add_f32 v[10:11], v[10:11], v[218:219]
	s_waitcnt vmcnt(4)
	v_pk_add_f32 v[12:13], v[12:13], v[220:221]
	v_pk_add_f32 v[14:15], v[14:15], v[222:223]
	s_waitcnt vmcnt(3)
	v_pk_add_f32 v[16:17], v[16:17], v[224:225]
	v_pk_add_f32 v[18:19], v[18:19], v[226:227]
	s_waitcnt vmcnt(2)
	v_pk_add_f32 v[20:21], v[20:21], v[228:229]
	v_pk_add_f32 v[22:23], v[22:23], v[230:231]
	s_waitcnt vmcnt(1)
	v_pk_add_f32 v[24:25], v[24:25], v[232:233]
	v_pk_add_f32 v[26:27], v[26:27], v[234:235]
	s_waitcnt vmcnt(0)
;     ...
;         if (nslab > 0 && m >= ML) {
; #pragma unroll
;             for (int j = 0; j < 8; ++j) v[j] = v[j] * ALPHA;
;             for (int sidx = 0; sidx < nslab; ++sidx) { const float* sp = slab + ((size_t)sidx * (2 * CTXL) + (m - ML)) * D + lane * 4;
; #pragma unroll
;                 for (int j = 0; j < 8; ++j) v[j] += *(const f32x4*)(sp + 256 * j); }
	v_pk_add_f32 v[28:29], v[28:29], v[236:237]
	v_pk_add_f32 v[30:31], v[30:31], v[238:239]
	s_add_u32 s24, s22, 0x800000
	s_addc_u32 s25, s23, 0
	s_add_u32 s26, s24, 0x1000
	s_addc_u32 s27, s25, 0
	global_load_dwordx4 v[176:179], v240, s[24:25]
	global_load_dwordx4 v[180:183], v240, s[24:25] offset:1024
	global_load_dwordx4 v[184:187], v240, s[24:25] offset:2048
	global_load_dwordx4 v[188:191], v240, s[24:25] offset:3072
	global_load_dwordx4 v[192:195], v240, s[26:27]
	global_load_dwordx4 v[196:199], v240, s[26:27] offset:1024
	global_load_dwordx4 v[200:203], v240, s[26:27] offset:2048
	global_load_dwordx4 v[204:207], v240, s[26:27] offset:3072
	s_add_u32 s28, s22, 0xc00000
	s_addc_u32 s29, s23, 0
	s_add_u32 s30, s28, 0x1000
	s_addc_u32 s31, s29, 0
	global_load_dwordx4 v[208:211], v240, s[28:29]
	global_load_dwordx4 v[212:215], v240, s[28:29] offset:1024
	global_load_dwordx4 v[216:219], v240, s[28:29] offset:2048
	global_load_dwordx4 v[220:223], v240, s[28:29] offset:3072
	global_load_dwordx4 v[224:227], v240, s[30:31]
	global_load_dwordx4 v[228:231], v240, s[30:31] offset:1024
	global_load_dwordx4 v[232:235], v240, s[30:31] offset:2048
	global_load_dwordx4 v[236:239], v240, s[30:31] offset:3072
	s_waitcnt vmcnt(15)
	v_pk_add_f32 v[0:1], v[0:1], v[176:177]
	v_pk_add_f32 v[2:3], v[2:3], v[178:179]
	s_waitcnt vmcnt(14)
	v_pk_add_f32 v[4:5], v[4:5], v[180:181]
	v_pk_add_f32 v[6:7], v[6:7], v[182:183]
	s_waitcnt vmcnt(13)
	v_pk_add_f32 v[8:9], v[8:9], v[184:185]
	v_pk_add_f32 v[10:11], v[10:11], v[186:187]
	s_waitcnt vmcnt(12)
	v_pk_add_f32 v[12:13], v[12:13], v[188:189]
	v_pk_add_f32 v[14:15], v[14:15], v[190:191]
	s_waitcnt vmcnt(11)
	v_pk_add_f32 v[16:17], v[16:17], v[192:193]
	v_pk_add_f32 v[18:19], v[18:19], v[194:195]
	s_waitcnt vmcnt(10)
	v_pk_add_f32 v[20:21], v[20:21], v[196:197]
	v_pk_add_f32 v[22:23], v[22:23], v[198:199]
	s_waitcnt vmcnt(9)
	v_pk_add_f32 v[24:25], v[24:25], v[200:201]
	v_pk_add_f32 v[26:27], v[26:27], v[202:203]
	s_waitcnt vmcnt(8)
	v_pk_add_f32 v[28:29], v[28:29], v[204:205]
	v_pk_add_f32 v[30:31], v[30:31], v[206:207]
	s_waitcnt vmcnt(7)
	v_pk_add_f32 v[0:1], v[0:1], v[208:209]
	v_pk_add_f32 v[2:3], v[2:3], v[210:211]
	s_waitcnt vmcnt(6)
	v_pk_add_f32 v[4:5], v[4:5], v[212:213]
	v_pk_add_f32 v[6:7], v[6:7], v[214:215]
	s_waitcnt vmcnt(5)
	v_pk_add_f32 v[8:9], v[8:9], v[216:217]
	v_pk_add_f32 v[10:11], v[10:11], v[218:219]
	s_waitcnt vmcnt(4)
	v_pk_add_f32 v[12:13], v[12:13], v[220:221]
	v_pk_add_f32 v[14:15], v[14:15], v[222:223]
	s_waitcnt vmcnt(3)
	v_pk_add_f32 v[16:17], v[16:17], v[224:225]
	v_pk_add_f32 v[18:19], v[18:19], v[226:227]
	s_waitcnt vmcnt(2)
	v_pk_add_f32 v[20:21], v[20:21], v[228:229]
	v_pk_add_f32 v[22:23], v[22:23], v[230:231]
	s_waitcnt vmcnt(1)
	v_pk_add_f32 v[24:25], v[24:25], v[232:233]
	v_pk_add_f32 v[26:27], v[26:27], v[234:235]
	s_waitcnt vmcnt(0)
	v_pk_add_f32 v[28:29], v[28:29], v[236:237]
	v_pk_add_f32 v[30:31], v[30:31], v[238:239]
	s_add_u32 s24, s22, 0x1000000
	s_addc_u32 s25, s23, 0
	s_add_u32 s26, s24, 0x1000
	s_addc_u32 s27, s25, 0
	global_load_dwordx4 v[176:179], v240, s[24:25]
	global_load_dwordx4 v[180:183], v240, s[24:25] offset:1024
	global_load_dwordx4 v[184:187], v240, s[24:25] offset:2048
	global_load_dwordx4 v[188:191], v240, s[24:25] offset:3072
	global_load_dwordx4 v[192:195], v240, s[26:27]
	global_load_dwordx4 v[196:199], v240, s[26:27] offset:1024
	global_load_dwordx4 v[200:203], v240, s[26:27] offset:2048
	global_load_dwordx4 v[204:207], v240, s[26:27] offset:3072
	s_add_u32 s28, s22, 0x1400000
	s_addc_u32 s29, s23, 0
	s_add_u32 s30, s28, 0x1000
	s_addc_u32 s31, s29, 0
	global_load_dwordx4 v[208:211], v240, s[28:29]
	global_load_dwordx4 v[212:215], v240, s[28:29] offset:1024
	global_load_dwordx4 v[216:219], v240, s[28:29] offset:2048
	global_load_dwordx4 v[220:223], v240, s[28:29] offset:3072
	global_load_dwordx4 v[224:227], v240, s[30:31]
	global_load_dwordx4 v[228:231], v240, s[30:31] offset:1024
	global_load_dwordx4 v[232:235], v240, s[30:31] offset:2048
	global_load_dwordx4 v[236:239], v240, s[30:31] offset:3072
	s_waitcnt vmcnt(15)
	v_pk_add_f32 v[0:1], v[0:1], v[176:177]
	v_pk_add_f32 v[2:3], v[2:3], v[178:179]
	s_waitcnt vmcnt(14)
	v_pk_add_f32 v[4:5], v[4:5], v[180:181]
	v_pk_add_f32 v[6:7], v[6:7], v[182:183]
	s_waitcnt vmcnt(13)
	v_pk_add_f32 v[8:9], v[8:9], v[184:185]
	v_pk_add_f32 v[10:11], v[10:11], v[186:187]
	s_waitcnt vmcnt(12)
	v_pk_add_f32 v[12:13], v[12:13], v[188:189]
	v_pk_add_f32 v[14:15], v[14:15], v[190:191]
	s_waitcnt vmcnt(11)
	v_pk_add_f32 v[16:17], v[16:17], v[192:193]
	v_pk_add_f32 v[18:19], v[18:19], v[194:195]
	s_waitcnt vmcnt(10)
	v_pk_add_f32 v[20:21], v[20:21], v[196:197]
	v_pk_add_f32 v[22:23], v[22:23], v[198:199]
	s_waitcnt vmcnt(9)
	v_pk_add_f32 v[24:25], v[24:25], v[200:201]
	v_pk_add_f32 v[26:27], v[26:27], v[202:203]
	s_waitcnt vmcnt(8)
	v_pk_add_f32 v[28:29], v[28:29], v[204:205]
	v_pk_add_f32 v[30:31], v[30:31], v[206:207]
	s_waitcnt vmcnt(7)
	v_pk_add_f32 v[0:1], v[0:1], v[208:209]
	v_pk_add_f32 v[2:3], v[2:3], v[210:211]
	s_waitcnt vmcnt(6)
	v_pk_add_f32 v[4:5], v[4:5], v[212:213]
	v_pk_add_f32 v[6:7], v[6:7], v[214:215]
	s_waitcnt vmcnt(5)
	v_pk_add_f32 v[8:9], v[8:9], v[216:217]
	v_pk_add_f32 v[10:11], v[10:11], v[218:219]
	s_waitcnt vmcnt(4)
	v_pk_add_f32 v[12:13], v[12:13], v[220:221]
	v_pk_add_f32 v[14:15], v[14:15], v[222:223]
	s_waitcnt vmcnt(3)
	v_pk_add_f32 v[16:17], v[16:17], v[224:225]
	v_pk_add_f32 v[18:19], v[18:19], v[226:227]
	s_waitcnt vmcnt(2)
	v_pk_add_f32 v[20:21], v[20:21], v[228:229]
	v_pk_add_f32 v[22:23], v[22:23], v[230:231]
	s_waitcnt vmcnt(1)
;     ...
;         if (nslab > 0 && m >= ML) {
; #pragma unroll
;             for (int j = 0; j < 8; ++j) v[j] = v[j] * ALPHA;
;             for (int sidx = 0; sidx < nslab; ++sidx) { const float* sp = slab + ((size_t)sidx * (2 * CTXL) + (m - ML)) * D + lane * 4;
; #pragma unroll
;                 for (int j = 0; j < 8; ++j) v[j] += *(const f32x4*)(sp + 256 * j); }
	v_pk_add_f32 v[24:25], v[24:25], v[232:233]
	v_pk_add_f32 v[26:27], v[26:27], v[234:235]
	s_waitcnt vmcnt(0)
	v_pk_add_f32 v[28:29], v[28:29], v[236:237]
	v_pk_add_f32 v[30:31], v[30:31], v[238:239]
	s_add_u32 s24, s22, 0x1800000
	s_addc_u32 s25, s23, 0
	s_add_u32 s26, s24, 0x1000
	s_addc_u32 s27, s25, 0
	global_load_dwordx4 v[176:179], v240, s[24:25]
	global_load_dwordx4 v[180:183], v240, s[24:25] offset:1024
	global_load_dwordx4 v[184:187], v240, s[24:25] offset:2048
	global_load_dwordx4 v[188:191], v240, s[24:25] offset:3072
	global_load_dwordx4 v[192:195], v240, s[26:27]
	global_load_dwordx4 v[196:199], v240, s[26:27] offset:1024
	global_load_dwordx4 v[200:203], v240, s[26:27] offset:2048
	global_load_dwordx4 v[204:207], v240, s[26:27] offset:3072
	s_add_u32 s28, s22, 0x1c00000
	s_addc_u32 s29, s23, 0
	s_add_u32 s30, s28, 0x1000
	s_addc_u32 s31, s29, 0
	global_load_dwordx4 v[208:211], v240, s[28:29]
	global_load_dwordx4 v[212:215], v240, s[28:29] offset:1024
	global_load_dwordx4 v[216:219], v240, s[28:29] offset:2048
	global_load_dwordx4 v[220:223], v240, s[28:29] offset:3072
	global_load_dwordx4 v[224:227], v240, s[30:31]
	global_load_dwordx4 v[228:231], v240, s[30:31] offset:1024
	global_load_dwordx4 v[232:235], v240, s[30:31] offset:2048
	global_load_dwordx4 v[236:239], v240, s[30:31] offset:3072
	s_waitcnt vmcnt(15)
	v_pk_add_f32 v[0:1], v[0:1], v[176:177]
	v_pk_add_f32 v[2:3], v[2:3], v[178:179]
	s_waitcnt vmcnt(14)
	v_pk_add_f32 v[4:5], v[4:5], v[180:181]
	v_pk_add_f32 v[6:7], v[6:7], v[182:183]
	s_waitcnt vmcnt(13)
	v_pk_add_f32 v[8:9], v[8:9], v[184:185]
	v_pk_add_f32 v[10:11], v[10:11], v[186:187]
	s_waitcnt vmcnt(12)
	v_pk_add_f32 v[12:13], v[12:13], v[188:189]
	v_pk_add_f32 v[14:15], v[14:15], v[190:191]
	s_waitcnt vmcnt(11)
	v_pk_add_f32 v[16:17], v[16:17], v[192:193]
	v_pk_add_f32 v[18:19], v[18:19], v[194:195]
	s_waitcnt vmcnt(10)
	v_pk_add_f32 v[20:21], v[20:21], v[196:197]
	v_pk_add_f32 v[22:23], v[22:23], v[198:199]
	s_waitcnt vmcnt(9)
	v_pk_add_f32 v[24:25], v[24:25], v[200:201]
	v_pk_add_f32 v[26:27], v[26:27], v[202:203]
	s_waitcnt vmcnt(8)
	v_pk_add_f32 v[28:29], v[28:29], v[204:205]
	v_pk_add_f32 v[30:31], v[30:31], v[206:207]
	s_waitcnt vmcnt(7)
	v_pk_add_f32 v[0:1], v[0:1], v[208:209]
	v_pk_add_f32 v[2:3], v[2:3], v[210:211]
	s_waitcnt vmcnt(6)
	v_pk_add_f32 v[4:5], v[4:5], v[212:213]
	v_pk_add_f32 v[6:7], v[6:7], v[214:215]
	s_waitcnt vmcnt(5)
	v_pk_add_f32 v[8:9], v[8:9], v[216:217]
	v_pk_add_f32 v[10:11], v[10:11], v[218:219]
	s_waitcnt vmcnt(4)
	v_pk_add_f32 v[12:13], v[12:13], v[220:221]
	v_pk_add_f32 v[14:15], v[14:15], v[222:223]
	s_waitcnt vmcnt(3)
	v_pk_add_f32 v[16:17], v[16:17], v[224:225]
	v_pk_add_f32 v[18:19], v[18:19], v[226:227]
	s_waitcnt vmcnt(2)
	v_pk_add_f32 v[20:21], v[20:21], v[228:229]
	v_pk_add_f32 v[22:23], v[22:23], v[230:231]
	s_waitcnt vmcnt(1)
	v_pk_add_f32 v[24:25], v[24:25], v[232:233]
	v_pk_add_f32 v[26:27], v[26:27], v[234:235]
	s_waitcnt vmcnt(0)
	v_pk_add_f32 v[28:29], v[28:29], v[236:237]
	v_pk_add_f32 v[30:31], v[30:31], v[238:239]
	s_add_u32 s24, s22, 0x2000000
	s_addc_u32 s25, s23, 0
	s_add_u32 s26, s24, 0x1000
	s_addc_u32 s27, s25, 0
	global_load_dwordx4 v[176:179], v240, s[24:25]
	global_load_dwordx4 v[180:183], v240, s[24:25] offset:1024
	global_load_dwordx4 v[184:187], v240, s[24:25] offset:2048
	global_load_dwordx4 v[188:191], v240, s[24:25] offset:3072
	global_load_dwordx4 v[192:195], v240, s[26:27]
	global_load_dwordx4 v[196:199], v240, s[26:27] offset:1024
	global_load_dwordx4 v[200:203], v240, s[26:27] offset:2048
	global_load_dwordx4 v[204:207], v240, s[26:27] offset:3072
	s_add_u32 s28, s22, 0x2400000
	s_addc_u32 s29, s23, 0
	s_add_u32 s30, s28, 0x1000
	s_addc_u32 s31, s29, 0
	global_load_dwordx4 v[208:211], v240, s[28:29]
	global_load_dwordx4 v[212:215], v240, s[28:29] offset:1024
	global_load_dwordx4 v[216:219], v240, s[28:29] offset:2048
	global_load_dwordx4 v[220:223], v240, s[28:29] offset:3072
	global_load_dwordx4 v[224:227], v240, s[30:31]
	global_load_dwordx4 v[228:231], v240, s[30:31] offset:1024
	global_load_dwordx4 v[232:235], v240, s[30:31] offset:2048
	global_load_dwordx4 v[236:239], v240, s[30:31] offset:3072
	s_waitcnt vmcnt(15)
	v_pk_add_f32 v[0:1], v[0:1], v[176:177]
	v_pk_add_f32 v[2:3], v[2:3], v[178:179]
	s_waitcnt vmcnt(14)
	v_pk_add_f32 v[4:5], v[4:5], v[180:181]
	v_pk_add_f32 v[6:7], v[6:7], v[182:183]
	s_waitcnt vmcnt(13)
	v_pk_add_f32 v[8:9], v[8:9], v[184:185]
	v_pk_add_f32 v[10:11], v[10:11], v[186:187]
	s_waitcnt vmcnt(12)
	v_pk_add_f32 v[12:13], v[12:13], v[188:189]
	v_pk_add_f32 v[14:15], v[14:15], v[190:191]
	s_waitcnt vmcnt(11)
	v_pk_add_f32 v[16:17], v[16:17], v[192:193]
	v_pk_add_f32 v[18:19], v[18:19], v[194:195]
	s_waitcnt vmcnt(10)
	v_pk_add_f32 v[20:21], v[20:21], v[196:197]
	v_pk_add_f32 v[22:23], v[22:23], v[198:199]
	s_waitcnt vmcnt(9)
	v_pk_add_f32 v[24:25], v[24:25], v[200:201]
	v_pk_add_f32 v[26:27], v[26:27], v[202:203]
	s_waitcnt vmcnt(8)
	v_pk_add_f32 v[28:29], v[28:29], v[204:205]
	v_pk_add_f32 v[30:31], v[30:31], v[206:207]
	s_waitcnt vmcnt(7)
	v_pk_add_f32 v[0:1], v[0:1], v[208:209]
	v_pk_add_f32 v[2:3], v[2:3], v[210:211]
	s_waitcnt vmcnt(6)
	v_pk_add_f32 v[4:5], v[4:5], v[212:213]
	v_pk_add_f32 v[6:7], v[6:7], v[214:215]
	s_waitcnt vmcnt(5)
	v_pk_add_f32 v[8:9], v[8:9], v[216:217]
	v_pk_add_f32 v[10:11], v[10:11], v[218:219]
	s_waitcnt vmcnt(4)
	v_pk_add_f32 v[12:13], v[12:13], v[220:221]
	v_pk_add_f32 v[14:15], v[14:15], v[222:223]
	s_waitcnt vmcnt(3)
	v_pk_add_f32 v[16:17], v[16:17], v[224:225]
	v_pk_add_f32 v[18:19], v[18:19], v[226:227]
	s_waitcnt vmcnt(2)
;     ...
;         if (nslab > 0 && m >= ML) {
; #pragma unroll
;             for (int j = 0; j < 8; ++j) v[j] = v[j] * ALPHA;
;             for (int sidx = 0; sidx < nslab; ++sidx) { const float* sp = slab + ((size_t)sidx * (2 * CTXL) + (m - ML)) * D + lane * 4;
; #pragma unroll
;                 for (int j = 0; j < 8; ++j) v[j] += *(const f32x4*)(sp + 256 * j); }
	v_pk_add_f32 v[20:21], v[20:21], v[228:229]
	v_pk_add_f32 v[22:23], v[22:23], v[230:231]
	s_waitcnt vmcnt(1)
	v_pk_add_f32 v[24:25], v[24:25], v[232:233]
	v_pk_add_f32 v[26:27], v[26:27], v[234:235]
	s_waitcnt vmcnt(0)
	v_pk_add_f32 v[28:29], v[28:29], v[236:237]
	v_pk_add_f32 v[30:31], v[30:31], v[238:239]
	s_add_u32 s24, s22, 0x2800000
	s_addc_u32 s25, s23, 0
	s_add_u32 s26, s24, 0x1000
	s_addc_u32 s27, s25, 0
	global_load_dwordx4 v[176:179], v240, s[24:25]
	global_load_dwordx4 v[180:183], v240, s[24:25] offset:1024
	global_load_dwordx4 v[184:187], v240, s[24:25] offset:2048
	global_load_dwordx4 v[188:191], v240, s[24:25] offset:3072
	global_load_dwordx4 v[192:195], v240, s[26:27]
	global_load_dwordx4 v[196:199], v240, s[26:27] offset:1024
	global_load_dwordx4 v[200:203], v240, s[26:27] offset:2048
	global_load_dwordx4 v[204:207], v240, s[26:27] offset:3072
	s_add_u32 s28, s22, 0x2c00000
	s_addc_u32 s29, s23, 0
	s_add_u32 s30, s28, 0x1000
	s_addc_u32 s31, s29, 0
	global_load_dwordx4 v[208:211], v240, s[28:29]
	global_load_dwordx4 v[212:215], v240, s[28:29] offset:1024
	global_load_dwordx4 v[216:219], v240, s[28:29] offset:2048
	global_load_dwordx4 v[220:223], v240, s[28:29] offset:3072
	global_load_dwordx4 v[224:227], v240, s[30:31]
	global_load_dwordx4 v[228:231], v240, s[30:31] offset:1024
	global_load_dwordx4 v[232:235], v240, s[30:31] offset:2048
	global_load_dwordx4 v[236:239], v240, s[30:31] offset:3072
	s_waitcnt vmcnt(15)
	v_pk_add_f32 v[0:1], v[0:1], v[176:177]
	v_pk_add_f32 v[2:3], v[2:3], v[178:179]
	s_waitcnt vmcnt(14)
	v_pk_add_f32 v[4:5], v[4:5], v[180:181]
	v_pk_add_f32 v[6:7], v[6:7], v[182:183]
	s_waitcnt vmcnt(13)
	v_pk_add_f32 v[8:9], v[8:9], v[184:185]
	v_pk_add_f32 v[10:11], v[10:11], v[186:187]
	s_waitcnt vmcnt(12)
	v_pk_add_f32 v[12:13], v[12:13], v[188:189]
	v_pk_add_f32 v[14:15], v[14:15], v[190:191]
	s_waitcnt vmcnt(11)
	v_pk_add_f32 v[16:17], v[16:17], v[192:193]
	v_pk_add_f32 v[18:19], v[18:19], v[194:195]
	s_waitcnt vmcnt(10)
	v_pk_add_f32 v[20:21], v[20:21], v[196:197]
	v_pk_add_f32 v[22:23], v[22:23], v[198:199]
	s_waitcnt vmcnt(9)
	v_pk_add_f32 v[24:25], v[24:25], v[200:201]
	v_pk_add_f32 v[26:27], v[26:27], v[202:203]
	s_waitcnt vmcnt(8)
	v_pk_add_f32 v[28:29], v[28:29], v[204:205]
	v_pk_add_f32 v[30:31], v[30:31], v[206:207]
	s_waitcnt vmcnt(7)
	v_pk_add_f32 v[0:1], v[0:1], v[208:209]
	v_pk_add_f32 v[2:3], v[2:3], v[210:211]
	s_waitcnt vmcnt(6)
	v_pk_add_f32 v[4:5], v[4:5], v[212:213]
	v_pk_add_f32 v[6:7], v[6:7], v[214:215]
	s_waitcnt vmcnt(5)
	v_pk_add_f32 v[8:9], v[8:9], v[216:217]
	v_pk_add_f32 v[10:11], v[10:11], v[218:219]
	s_waitcnt vmcnt(4)
	v_pk_add_f32 v[12:13], v[12:13], v[220:221]
	v_pk_add_f32 v[14:15], v[14:15], v[222:223]
	s_waitcnt vmcnt(3)
	v_pk_add_f32 v[16:17], v[16:17], v[224:225]
	v_pk_add_f32 v[18:19], v[18:19], v[226:227]
	s_waitcnt vmcnt(2)
	v_pk_add_f32 v[20:21], v[20:21], v[228:229]
	v_pk_add_f32 v[22:23], v[22:23], v[230:231]
	s_waitcnt vmcnt(1)
	v_pk_add_f32 v[24:25], v[24:25], v[232:233]
	v_pk_add_f32 v[26:27], v[26:27], v[234:235]
	s_waitcnt vmcnt(0)
	v_pk_add_f32 v[28:29], v[28:29], v[236:237]
	v_pk_add_f32 v[30:31], v[30:31], v[238:239]
	s_add_u32 s24, s22, 0x3000000
	s_addc_u32 s25, s23, 0
	s_add_u32 s26, s24, 0x1000
	s_addc_u32 s27, s25, 0
	global_load_dwordx4 v[176:179], v240, s[24:25]
	global_load_dwordx4 v[180:183], v240, s[24:25] offset:1024
	global_load_dwordx4 v[184:187], v240, s[24:25] offset:2048
	global_load_dwordx4 v[188:191], v240, s[24:25] offset:3072
	global_load_dwordx4 v[192:195], v240, s[26:27]
	global_load_dwordx4 v[196:199], v240, s[26:27] offset:1024
	global_load_dwordx4 v[200:203], v240, s[26:27] offset:2048
	global_load_dwordx4 v[204:207], v240, s[26:27] offset:3072
	s_add_u32 s28, s22, 0x3400000
	s_addc_u32 s29, s23, 0
	s_add_u32 s30, s28, 0x1000
	s_addc_u32 s31, s29, 0
	global_load_dwordx4 v[208:211], v240, s[28:29]
	global_load_dwordx4 v[212:215], v240, s[28:29] offset:1024
	global_load_dwordx4 v[216:219], v240, s[28:29] offset:2048
	global_load_dwordx4 v[220:223], v240, s[28:29] offset:3072
	global_load_dwordx4 v[224:227], v240, s[30:31]
	global_load_dwordx4 v[228:231], v240, s[30:31] offset:1024
	global_load_dwordx4 v[232:235], v240, s[30:31] offset:2048
	global_load_dwordx4 v[236:239], v240, s[30:31] offset:3072
	s_waitcnt vmcnt(15)
	v_pk_add_f32 v[0:1], v[0:1], v[176:177]
	v_pk_add_f32 v[2:3], v[2:3], v[178:179]
	s_waitcnt vmcnt(14)
	v_pk_add_f32 v[4:5], v[4:5], v[180:181]
	v_pk_add_f32 v[6:7], v[6:7], v[182:183]
	s_waitcnt vmcnt(13)
	v_pk_add_f32 v[8:9], v[8:9], v[184:185]
	v_pk_add_f32 v[10:11], v[10:11], v[186:187]
	s_waitcnt vmcnt(12)
	v_pk_add_f32 v[12:13], v[12:13], v[188:189]
	v_pk_add_f32 v[14:15], v[14:15], v[190:191]
	s_waitcnt vmcnt(11)
	v_pk_add_f32 v[16:17], v[16:17], v[192:193]
	v_pk_add_f32 v[18:19], v[18:19], v[194:195]
	s_waitcnt vmcnt(10)
	v_pk_add_f32 v[20:21], v[20:21], v[196:197]
	v_pk_add_f32 v[22:23], v[22:23], v[198:199]
	s_waitcnt vmcnt(9)
	v_pk_add_f32 v[24:25], v[24:25], v[200:201]
	v_pk_add_f32 v[26:27], v[26:27], v[202:203]
	s_waitcnt vmcnt(8)
	v_pk_add_f32 v[28:29], v[28:29], v[204:205]
	v_pk_add_f32 v[30:31], v[30:31], v[206:207]
	s_waitcnt vmcnt(7)
	v_pk_add_f32 v[0:1], v[0:1], v[208:209]
	v_pk_add_f32 v[2:3], v[2:3], v[210:211]
	s_waitcnt vmcnt(6)
	v_pk_add_f32 v[4:5], v[4:5], v[212:213]
	v_pk_add_f32 v[6:7], v[6:7], v[214:215]
	s_waitcnt vmcnt(5)
	v_pk_add_f32 v[8:9], v[8:9], v[216:217]
	v_pk_add_f32 v[10:11], v[10:11], v[218:219]
	s_waitcnt vmcnt(4)
	v_pk_add_f32 v[12:13], v[12:13], v[220:221]
	v_pk_add_f32 v[14:15], v[14:15], v[222:223]
	s_waitcnt vmcnt(3)
;     ...
;             for (int sidx = 0; sidx < nslab; ++sidx) { const float* sp = slab + ((size_t)sidx * (2 * CTXL) + (m - ML)) * D + lane * 4;
; #pragma unroll
;                 for (int j = 0; j < 8; ++j) v[j] += *(const f32x4*)(sp + 256 * j); }
;         }
;         if (do_ln) {
;             float s = 0.f;
; #pragma unroll
;             for (int j = 0; j < 8; ++j) s += (v[j].x + v[j].y) + (v[j].z + v[j].w);
;             const float mean = wave_sum(s) * (1.f / D); float s2 = 0.f;
;     ...
;             const float* sh = modl + mv * NMOD + shc * D; const float* sc = modl + mv * NMOD + scc * D;
	v_pk_add_f32 v[16:17], v[16:17], v[224:225]
	v_pk_add_f32 v[18:19], v[18:19], v[226:227]
	s_waitcnt vmcnt(2)
	v_pk_add_f32 v[20:21], v[20:21], v[228:229]
	v_pk_add_f32 v[22:23], v[22:23], v[230:231]
	s_waitcnt vmcnt(1)
	v_pk_add_f32 v[24:25], v[24:25], v[232:233]
	v_pk_add_f32 v[26:27], v[26:27], v[234:235]
	s_waitcnt vmcnt(0)
	v_pk_add_f32 v[28:29], v[28:29], v[236:237]
	v_pk_add_f32 v[30:31], v[30:31], v[238:239]
	s_add_u32 s24, s22, 0x3800000
	s_addc_u32 s25, s23, 0
	s_add_u32 s26, s24, 0x1000
	s_addc_u32 s27, s25, 0
	global_load_dwordx4 v[176:179], v240, s[24:25]
	global_load_dwordx4 v[180:183], v240, s[24:25] offset:1024
	global_load_dwordx4 v[184:187], v240, s[24:25] offset:2048
	global_load_dwordx4 v[188:191], v240, s[24:25] offset:3072
	global_load_dwordx4 v[192:195], v240, s[26:27]
	global_load_dwordx4 v[196:199], v240, s[26:27] offset:1024
	global_load_dwordx4 v[200:203], v240, s[26:27] offset:2048
	global_load_dwordx4 v[204:207], v240, s[26:27] offset:3072
	s_add_u32 s28, s22, 0x3c00000
	s_addc_u32 s29, s23, 0
	s_add_u32 s30, s28, 0x1000
	s_addc_u32 s31, s29, 0
	global_load_dwordx4 v[208:211], v240, s[28:29]
	global_load_dwordx4 v[212:215], v240, s[28:29] offset:1024
	global_load_dwordx4 v[216:219], v240, s[28:29] offset:2048
	global_load_dwordx4 v[220:223], v240, s[28:29] offset:3072
	global_load_dwordx4 v[224:227], v240, s[30:31]
	global_load_dwordx4 v[228:231], v240, s[30:31] offset:1024
	global_load_dwordx4 v[232:235], v240, s[30:31] offset:2048
	global_load_dwordx4 v[236:239], v240, s[30:31] offset:3072
	s_waitcnt vmcnt(15)
	v_pk_add_f32 v[0:1], v[0:1], v[176:177]
	v_pk_add_f32 v[2:3], v[2:3], v[178:179]
	s_waitcnt vmcnt(14)
	v_pk_add_f32 v[4:5], v[4:5], v[180:181]
	v_pk_add_f32 v[6:7], v[6:7], v[182:183]
	s_waitcnt vmcnt(13)
	v_pk_add_f32 v[8:9], v[8:9], v[184:185]
	v_pk_add_f32 v[10:11], v[10:11], v[186:187]
	s_waitcnt vmcnt(12)
	v_pk_add_f32 v[12:13], v[12:13], v[188:189]
	v_pk_add_f32 v[14:15], v[14:15], v[190:191]
	s_waitcnt vmcnt(11)
	v_pk_add_f32 v[16:17], v[16:17], v[192:193]
	v_pk_add_f32 v[18:19], v[18:19], v[194:195]
	s_waitcnt vmcnt(10)
	v_pk_add_f32 v[20:21], v[20:21], v[196:197]
	v_pk_add_f32 v[22:23], v[22:23], v[198:199]
	s_waitcnt vmcnt(9)
	v_pk_add_f32 v[24:25], v[24:25], v[200:201]
	v_pk_add_f32 v[26:27], v[26:27], v[202:203]
	s_waitcnt vmcnt(8)
	v_pk_add_f32 v[28:29], v[28:29], v[204:205]
	v_pk_add_f32 v[30:31], v[30:31], v[206:207]
	s_waitcnt vmcnt(7)
	v_pk_add_f32 v[0:1], v[0:1], v[208:209]
	v_pk_add_f32 v[2:3], v[2:3], v[210:211]
	s_waitcnt vmcnt(6)
	v_pk_add_f32 v[4:5], v[4:5], v[212:213]
	v_pk_add_f32 v[6:7], v[6:7], v[214:215]
	s_waitcnt vmcnt(5)
	v_pk_add_f32 v[8:9], v[8:9], v[216:217]
	v_pk_add_f32 v[10:11], v[10:11], v[218:219]
	s_waitcnt vmcnt(4)
	v_pk_add_f32 v[12:13], v[12:13], v[220:221]
	v_pk_add_f32 v[14:15], v[14:15], v[222:223]
	s_waitcnt vmcnt(3)
	v_pk_add_f32 v[16:17], v[16:17], v[224:225]
	v_pk_add_f32 v[18:19], v[18:19], v[226:227]
	s_waitcnt vmcnt(2)
	v_pk_add_f32 v[20:21], v[20:21], v[228:229]
	v_pk_add_f32 v[22:23], v[22:23], v[230:231]
	s_waitcnt vmcnt(1)
	v_pk_add_f32 v[24:25], v[24:25], v[232:233]
	v_pk_add_f32 v[26:27], v[26:27], v[234:235]
	s_waitcnt vmcnt(0)
	v_pk_add_f32 v[28:29], v[28:29], v[236:237]
	v_pk_add_f32 v[30:31], v[30:31], v[238:239]
	v_mov_b32_e32 v226, 0x3a000000
	v_mov_b32_e32 v227, 0x3727c5ac
	s_add_u32 s10, s64, 0x3c000
	s_addc_u32 s11, s65, 0
	s_add_u32 s12, s10, 0x1000
	s_addc_u32 s13, s11, 0
	s_add_u32 s14, s64, 0x3e000
	s_addc_u32 s15, s65, 0
	s_add_u32 s16, s14, 0x1000
	s_addc_u32 s17, s15, 0
	global_load_dwordx4 v[176:179], v240, s[10:11]
	global_load_dwordx4 v[180:183], v240, s[10:11] offset:1024
	global_load_dwordx4 v[184:187], v240, s[10:11] offset:2048
	global_load_dwordx4 v[188:191], v240, s[10:11] offset:3072
	global_load_dwordx4 v[192:195], v240, s[12:13]
	global_load_dwordx4 v[196:199], v240, s[12:13] offset:1024
	global_load_dwordx4 v[200:203], v240, s[12:13] offset:2048
	global_load_dwordx4 v[204:207], v240, s[12:13] offset:3072
	global_load_dwordx4 v[32:35], v240, s[14:15]
	global_load_dwordx4 v[36:39], v240, s[14:15] offset:1024
	global_load_dwordx4 v[40:43], v240, s[14:15] offset:2048
	global_load_dwordx4 v[44:47], v240, s[14:15] offset:3072
	global_load_dwordx4 v[48:51], v240, s[16:17]
	global_load_dwordx4 v[52:55], v240, s[16:17] offset:1024
	global_load_dwordx4 v[56:59], v240, s[16:17] offset:2048
	global_load_dwordx4 v[60:63], v240, s[16:17] offset:3072
	s_add_u32 s84, s64, 0x6300000
	s_addc_u32 s85, s65, 0
	s_add_u32 s84, s84, s58
	s_addc_u32 s85, s85, 0
	s_add_u32 s86, s84, 0x1000
	s_addc_u32 s87, s85, 0
	s_add_i32 s59, s60, 0x4000
	s_lshl_b32 s59, s59, 12
	s_add_u32 s96, s64, 0x6700000
	s_addc_u32 s97, s65, 0
	s_add_u32 s96, s96, s59
	s_addc_u32 s97, s97, 0
	v_pk_add_f32 v[208:209], v[0:1], v[2:3]
	v_pk_add_f32 v[210:211], v[4:5], v[6:7]
	v_pk_add_f32 v[212:213], v[8:9], v[10:11]
	v_pk_add_f32 v[214:215], v[12:13], v[14:15]
	v_pk_add_f32 v[216:217], v[16:17], v[18:19]
	v_pk_add_f32 v[218:219], v[20:21], v[22:23]
	v_pk_add_f32 v[220:221], v[24:25], v[26:27]
	v_pk_add_f32 v[222:223], v[28:29], v[30:31]
	v_pk_add_f32 v[208:209], v[208:209], v[210:211]
	v_pk_add_f32 v[212:213], v[212:213], v[214:215]
	v_pk_add_f32 v[216:217], v[216:217], v[218:219]
	v_pk_add_f32 v[220:221], v[220:221], v[222:223]
	v_pk_add_f32 v[208:209], v[208:209], v[212:213]
	v_pk_add_f32 v[216:217], v[216:217], v[220:221]
	v_pk_add_f32 v[208:209], v[208:209], v[216:217]
	v_add_f32_e32 v242, v208, v209
	s_nop 1
	v_add_f32_dpp v242, v242, v242 row_ror:8 row_mask:0xf bank_mask:0xf bound_ctrl:1
	s_nop 1
	v_add_f32_dpp v242, v242, v242 row_ror:4 row_mask:0xf bank_mask:0xf bound_ctrl:1
;     ...
;             for (int j = 0; j < 8; ++j) s += (v[j].x + v[j].y) + (v[j].z + v[j].w);
;             const float mean = wave_sum(s) * (1.f / D); float s2 = 0.f;
; #pragma unroll
;             for (int j = 0; j < 8; ++j) { v[j] = v[j] - mean; s2 += (v[j].x * v[j].x + v[j].y * v[j].y) + (v[j].z * v[j].z + v[j].w * v[j].w); }
;             const float rstd = rsqrtf(wave_sum(s2) * (1.f / D) + LN_EPS);
	s_nop 1
	v_add_f32_dpp v242, v242, v242 row_ror:2 row_mask:0xf bank_mask:0xf bound_ctrl:1
	s_nop 1
	v_add_f32_dpp v242, v242, v242 row_ror:1 row_mask:0xf bank_mask:0xf bound_ctrl:1
	s_nop 1
	v_readlane_b32 s52, v242, 0
	v_readlane_b32 s53, v242, 16
	v_readlane_b32 s54, v242, 32
	v_readlane_b32 s55, v242, 48
	s_nop 1
	v_mov_b32_e32 v243, s52
	v_add_f32_e32 v243, s53, v243
	v_add_f32_e32 v243, s54, v243
	v_add_f32_e32 v243, s55, v243
	v_mul_f32_e32 v244, v226, v243
	v_pk_add_f32 v[0:1], v[0:1], v[244:245] op_sel_hi:[1,0] neg_lo:[0,1] neg_hi:[0,1]
	v_pk_add_f32 v[2:3], v[2:3], v[244:245] op_sel_hi:[1,0] neg_lo:[0,1] neg_hi:[0,1]
	v_pk_add_f32 v[4:5], v[4:5], v[244:245] op_sel_hi:[1,0] neg_lo:[0,1] neg_hi:[0,1]
	v_pk_add_f32 v[6:7], v[6:7], v[244:245] op_sel_hi:[1,0] neg_lo:[0,1] neg_hi:[0,1]
	v_pk_add_f32 v[8:9], v[8:9], v[244:245] op_sel_hi:[1,0] neg_lo:[0,1] neg_hi:[0,1]
	v_pk_add_f32 v[10:11], v[10:11], v[244:245] op_sel_hi:[1,0] neg_lo:[0,1] neg_hi:[0,1]
	v_pk_add_f32 v[12:13], v[12:13], v[244:245] op_sel_hi:[1,0] neg_lo:[0,1] neg_hi:[0,1]
	v_pk_add_f32 v[14:15], v[14:15], v[244:245] op_sel_hi:[1,0] neg_lo:[0,1] neg_hi:[0,1]
	v_pk_add_f32 v[16:17], v[16:17], v[244:245] op_sel_hi:[1,0] neg_lo:[0,1] neg_hi:[0,1]
	v_pk_add_f32 v[18:19], v[18:19], v[244:245] op_sel_hi:[1,0] neg_lo:[0,1] neg_hi:[0,1]
	v_pk_add_f32 v[20:21], v[20:21], v[244:245] op_sel_hi:[1,0] neg_lo:[0,1] neg_hi:[0,1]
	v_pk_add_f32 v[22:23], v[22:23], v[244:245] op_sel_hi:[1,0] neg_lo:[0,1] neg_hi:[0,1]
	v_pk_add_f32 v[24:25], v[24:25], v[244:245] op_sel_hi:[1,0] neg_lo:[0,1] neg_hi:[0,1]
	v_pk_add_f32 v[26:27], v[26:27], v[244:245] op_sel_hi:[1,0] neg_lo:[0,1] neg_hi:[0,1]
	v_pk_add_f32 v[28:29], v[28:29], v[244:245] op_sel_hi:[1,0] neg_lo:[0,1] neg_hi:[0,1]
	v_pk_add_f32 v[30:31], v[30:31], v[244:245] op_sel_hi:[1,0] neg_lo:[0,1] neg_hi:[0,1]
	v_pk_mul_f32 v[208:209], v[0:1], v[0:1]
	v_pk_mul_f32 v[210:211], v[2:3], v[2:3]
	v_pk_mul_f32 v[212:213], v[4:5], v[4:5]
	v_pk_mul_f32 v[214:215], v[6:7], v[6:7]
	v_pk_fma_f32 v[208:209], v[8:9], v[8:9], v[208:209]
	v_pk_fma_f32 v[210:211], v[10:11], v[10:11], v[210:211]
	v_pk_fma_f32 v[212:213], v[12:13], v[12:13], v[212:213]
	v_pk_fma_f32 v[214:215], v[14:15], v[14:15], v[214:215]
	v_pk_fma_f32 v[208:209], v[16:17], v[16:17], v[208:209]
	v_pk_fma_f32 v[210:211], v[18:19], v[18:19], v[210:211]
	v_pk_fma_f32 v[212:213], v[20:21], v[20:21], v[212:213]
	v_pk_fma_f32 v[214:215], v[22:23], v[22:23], v[214:215]
	v_pk_fma_f32 v[208:209], v[24:25], v[24:25], v[208:209]
	v_pk_fma_f32 v[210:211], v[26:27], v[26:27], v[210:211]
	v_pk_fma_f32 v[212:213], v[28:29], v[28:29], v[212:213]
	v_pk_fma_f32 v[214:215], v[30:31], v[30:31], v[214:215]
	v_pk_add_f32 v[208:209], v[208:209], v[210:211]
	v_pk_add_f32 v[212:213], v[212:213], v[214:215]
	v_pk_add_f32 v[208:209], v[208:209], v[212:213]
	v_add_f32_e32 v242, v208, v209
	s_nop 1
	v_add_f32_dpp v242, v242, v242 row_ror:8 row_mask:0xf bank_mask:0xf bound_ctrl:1
	s_nop 1
	v_add_f32_dpp v242, v242, v242 row_ror:4 row_mask:0xf bank_mask:0xf bound_ctrl:1
	s_nop 1
	v_add_f32_dpp v242, v242, v242 row_ror:2 row_mask:0xf bank_mask:0xf bound_ctrl:1
	s_nop 1
	v_add_f32_dpp v242, v242, v242 row_ror:1 row_mask:0xf bank_mask:0xf bound_ctrl:1
	s_nop 1
	v_readlane_b32 s52, v242, 0
	v_readlane_b32 s53, v242, 16
	v_readlane_b32 s54, v242, 32
	v_readlane_b32 s55, v242, 48
	s_nop 1
	v_mov_b32_e32 v243, s52
	v_add_f32_e32 v243, s53, v243
	v_add_f32_e32 v243, s54, v243
	v_add_f32_e32 v243, s55, v243
	v_fma_f32 v224, v243, v226, v227
	v_rsq_f32_e32 v224, v224
	s_waitcnt vmcnt(0)
; __device__ __forceinline__ unsigned pk2(float lo, float hi) { return f2bf(lo) | (f2bf(hi) << 16); }
;     ...
;             const float rstd = rsqrtf(wave_sum(s2) * (1.f / D) + LN_EPS);
; #pragma unroll
;             for (int j = 0; j < 8; ++j) { const f32x4 gg = *(const f32x4*)(lng + lane * 4 + 256 * j), bb = *(const f32x4*)(lnb + lane * 4 + 256 * j);
;                 v[j] = v[j] * rstd * gg + bb; *(f32x4*)(dst + lane * 4 + 256 * j) = v[j]; }
;         }
;         if (do_mod) {
;             const float* sh = modl + mv * NMOD + shc * D; const float* sc = modl + mv * NMOD + scc * D;
; #pragma unroll
;             for (int j = 0; j < 8; ++j) { const f32x4 s1 = *(const f32x4*)(sc + lane * 4 + 256 * j), h1 = *(const f32x4*)(sh + lane * 4 + 256 * j);
;                 const f32x4 a = v[j] * (s1 + 1.f) + h1; u32x2 o; o.x = pk2(a.x, a.y); o.y = pk2(a.z, a.w);
;                 *(u32x2*)(aout + (size_t)m * D + lane * 4 + 256 * j) = o; }
	v_pk_add_f32 v[32:33], v[32:33], 1.0 op_sel_hi:[1,0]
	v_pk_add_f32 v[34:35], v[34:35], 1.0 op_sel_hi:[1,0]
	v_pk_add_f32 v[36:37], v[36:37], 1.0 op_sel_hi:[1,0]
	v_pk_add_f32 v[38:39], v[38:39], 1.0 op_sel_hi:[1,0]
	v_pk_add_f32 v[40:41], v[40:41], 1.0 op_sel_hi:[1,0]
	v_pk_add_f32 v[42:43], v[42:43], 1.0 op_sel_hi:[1,0]
	v_pk_add_f32 v[44:45], v[44:45], 1.0 op_sel_hi:[1,0]
	v_pk_add_f32 v[46:47], v[46:47], 1.0 op_sel_hi:[1,0]
	v_pk_add_f32 v[48:49], v[48:49], 1.0 op_sel_hi:[1,0]
	v_pk_add_f32 v[50:51], v[50:51], 1.0 op_sel_hi:[1,0]
	v_pk_add_f32 v[52:53], v[52:53], 1.0 op_sel_hi:[1,0]
	v_pk_add_f32 v[54:55], v[54:55], 1.0 op_sel_hi:[1,0]
	v_pk_add_f32 v[56:57], v[56:57], 1.0 op_sel_hi:[1,0]
	v_pk_add_f32 v[58:59], v[58:59], 1.0 op_sel_hi:[1,0]
	v_pk_add_f32 v[60:61], v[60:61], 1.0 op_sel_hi:[1,0]
	v_pk_add_f32 v[62:63], v[62:63], 1.0 op_sel_hi:[1,0]
	v_pk_mul_f32 v[208:209], v[0:1], v[224:225] op_sel_hi:[1,0]
	v_pk_mul_f32 v[210:211], v[2:3], v[224:225] op_sel_hi:[1,0]
	v_pk_fma_f32 v[0:1], v[208:209], v[96:97], v[128:129]
	v_pk_fma_f32 v[2:3], v[210:211], v[98:99], v[130:131]
	global_store_dwordx4 v240, v[0:3], s[84:85]
	v_pk_mul_f32 v[208:209], v[4:5], v[224:225] op_sel_hi:[1,0]
	v_pk_mul_f32 v[210:211], v[6:7], v[224:225] op_sel_hi:[1,0]
	v_pk_fma_f32 v[4:5], v[208:209], v[100:101], v[132:133]
	v_pk_fma_f32 v[6:7], v[210:211], v[102:103], v[134:135]
	global_store_dwordx4 v240, v[4:7], s[84:85] offset:1024
	v_pk_mul_f32 v[208:209], v[8:9], v[224:225] op_sel_hi:[1,0]
	v_pk_mul_f32 v[210:211], v[10:11], v[224:225] op_sel_hi:[1,0]
	v_pk_fma_f32 v[8:9], v[208:209], v[104:105], v[136:137]
	v_pk_fma_f32 v[10:11], v[210:211], v[106:107], v[138:139]
	global_store_dwordx4 v240, v[8:11], s[84:85] offset:2048
	v_pk_mul_f32 v[208:209], v[12:13], v[224:225] op_sel_hi:[1,0]
	v_pk_mul_f32 v[210:211], v[14:15], v[224:225] op_sel_hi:[1,0]
	v_pk_fma_f32 v[12:13], v[208:209], v[108:109], v[140:141]
	v_pk_fma_f32 v[14:15], v[210:211], v[110:111], v[142:143]
	global_store_dwordx4 v240, v[12:15], s[84:85] offset:3072
	v_pk_mul_f32 v[208:209], v[16:17], v[224:225] op_sel_hi:[1,0]
	v_pk_mul_f32 v[210:211], v[18:19], v[224:225] op_sel_hi:[1,0]
	v_pk_fma_f32 v[16:17], v[208:209], v[112:113], v[144:145]
	v_pk_fma_f32 v[18:19], v[210:211], v[114:115], v[146:147]
	global_store_dwordx4 v240, v[16:19], s[86:87]
	v_pk_mul_f32 v[208:209], v[20:21], v[224:225] op_sel_hi:[1,0]
	v_pk_mul_f32 v[210:211], v[22:23], v[224:225] op_sel_hi:[1,0]
	v_pk_fma_f32 v[20:21], v[208:209], v[116:117], v[148:149]
	v_pk_fma_f32 v[22:23], v[210:211], v[118:119], v[150:151]
	global_store_dwordx4 v240, v[20:23], s[86:87] offset:1024
	v_pk_mul_f32 v[208:209], v[24:25], v[224:225] op_sel_hi:[1,0]
	v_pk_mul_f32 v[210:211], v[26:27], v[224:225] op_sel_hi:[1,0]
	v_pk_fma_f32 v[24:25], v[208:209], v[120:121], v[152:153]
	v_pk_fma_f32 v[26:27], v[210:211], v[122:123], v[154:155]
	global_store_dwordx4 v240, v[24:27], s[86:87] offset:2048
	v_pk_mul_f32 v[208:209], v[28:29], v[224:225] op_sel_hi:[1,0]
	v_pk_mul_f32 v[210:211], v[30:31], v[224:225] op_sel_hi:[1,0]
	v_pk_fma_f32 v[28:29], v[208:209], v[124:125], v[156:157]
	v_pk_fma_f32 v[30:31], v[210:211], v[126:127], v[158:159]
	global_store_dwordx4 v240, v[28:31], s[86:87] offset:3072
	v_pk_fma_f32 v[208:209], v[0:1], v[32:33], v[176:177]
	v_pk_fma_f32 v[210:211], v[2:3], v[34:35], v[178:179]
	v_cvt_pk_bf16_f32 v212, v208, v209
	v_cvt_pk_bf16_f32 v213, v210, v211
	global_store_dwordx2 v241, v[212:213], s[96:97]
	v_pk_fma_f32 v[208:209], v[4:5], v[36:37], v[180:181]
	v_pk_fma_f32 v[210:211], v[6:7], v[38:39], v[182:183]
	v_cvt_pk_bf16_f32 v212, v208, v209
	v_cvt_pk_bf16_f32 v213, v210, v211
	global_store_dwordx2 v241, v[212:213], s[96:97] offset:512
	v_pk_fma_f32 v[208:209], v[8:9], v[40:41], v[184:185]
	v_pk_fma_f32 v[210:211], v[10:11], v[42:43], v[186:187]
	v_cvt_pk_bf16_f32 v212, v208, v209
	v_cvt_pk_bf16_f32 v213, v210, v211
	global_store_dwordx2 v241, v[212:213], s[96:97] offset:1024
	v_pk_fma_f32 v[208:209], v[12:13], v[44:45], v[188:189]
	v_pk_fma_f32 v[210:211], v[14:15], v[46:47], v[190:191]
	v_cvt_pk_bf16_f32 v212, v208, v209
	v_cvt_pk_bf16_f32 v213, v210, v211
	global_store_dwordx2 v241, v[212:213], s[96:97] offset:1536
	v_pk_fma_f32 v[208:209], v[16:17], v[48:49], v[192:193]
	v_pk_fma_f32 v[210:211], v[18:19], v[50:51], v[194:195]
	v_cvt_pk_bf16_f32 v212, v208, v209
	v_cvt_pk_bf16_f32 v213, v210, v211
	global_store_dwordx2 v241, v[212:213], s[96:97] offset:2048
	v_pk_fma_f32 v[208:209], v[20:21], v[52:53], v[196:197]
	v_pk_fma_f32 v[210:211], v[22:23], v[54:55], v[198:199]
	v_cvt_pk_bf16_f32 v212, v208, v209
	v_cvt_pk_bf16_f32 v213, v210, v211
	global_store_dwordx2 v241, v[212:213], s[96:97] offset:2560
	v_pk_fma_f32 v[208:209], v[24:25], v[56:57], v[200:201]
	v_pk_fma_f32 v[210:211], v[26:27], v[58:59], v[202:203]
	v_cvt_pk_bf16_f32 v212, v208, v209
	v_cvt_pk_bf16_f32 v213, v210, v211
	global_store_dwordx2 v241, v[212:213], s[96:97] offset:3072
	v_pk_fma_f32 v[208:209], v[28:29], v[60:61], v[204:205]
	v_pk_fma_f32 v[210:211], v[30:31], v[62:63], v[206:207]
	v_cvt_pk_bf16_f32 v212, v208, v209
	v_cvt_pk_bf16_f32 v213, v210, v211
	global_store_dwordx2 v241, v[212:213], s[96:97] offset:3584
	s_nop 1

;     __device__ __forceinline__ void operator()(const pg8::f32x4 (&acc)[2][2][4][2], const pg8::Unit& u, int wr, int wc, int fr, int fq) const {
;         const int R0 = u.pm * 256; const float* src; float* dst; int mv;
;         if (R0 < ML) { src = srcL + (size_t)R0 * D; dst = dstL + (size_t)R0 * D; mv = (R0 >= SEQ) ? 1 : 0; }
;         else { src = srcC + (size_t)(R0 - ML) * D; dst = dstC + (size_t)(R0 - ML) * D; mv = 2; }
;         const int col0 = u.pn * 256 + wc * 32 + 4 * fq; const float* gt = gate + mv * NMOD + col0;
;         pg8::f32x4 gv[2][2];
; #pragma unroll
;         for (int bj = 0; bj < 2; ++bj)
; #pragma unroll
;             for (int n = 0; n < 2; ++n) gv[bj][n] = *(const pg8::f32x4*)(gt + bj * 128 + n * 16);
; #pragma unroll
;         for (int ai = 0; ai < 2; ++ai)
; #pragma unroll
;             for (int m = 0; m < 4; ++m) { const size_t off = (size_t)(wr * 64 + fr + ai * 128 + m * 16) * D + col0;
; #pragma unroll
;                 for (int bj = 0; bj < 2; ++bj)
; #pragma unroll
;                     for (int n = 0; n < 2; ++n) { const pg8::f32x4 s = *(const pg8::f32x4*)(src + off + bj * 128 + n * 16);
;                         *(pg8::f32x4*)(dst + off + bj * 128 + n * 16) = s * ALPHA + gv[bj][n] * acc[ai][bj][m][n]; }
;                 asm volatile("" ::: "memory"); }
.LBB0_1772:
	v_lshl_or_b32 v128, s53, 8, v176
	v_ashrrev_i32_e32 v129, 31, v128
	v_lshlrev_b64 v[172:173], 2, v[128:129]
	s_lshl_b32 s2, s38, 2
	s_add_u32 s36, s44, s2
	s_addc_u32 s37, s45, 0
	v_lshl_add_u64 v[128:129], s[36:37], 0, v[172:173]
	global_load_dwordx4 v[140:143], v[128:129], off
	global_load_dwordx4 v[136:139], v[128:129], off offset:64
	global_load_dwordx4 v[132:135], v[128:129], off offset:512
	s_nop 0
	global_load_dwordx4 v[128:131], v[128:129], off offset:576
	s_andn2_b64 vcc, exec, s[0:1]
	s_mov_b64 s[0:1], -1
	v_lshl_add_u64 v[224:225], s[34:35], 0, v[148:149]
	v_lshl_add_u64 v[224:225], v[224:225], 0, v[172:173]
	global_load_dwordx4 v[180:183], v[224:225], off
	global_load_dwordx4 v[184:187], v[224:225], off offset:64
	global_load_dwordx4 v[188:191], v[224:225], off offset:512
	global_load_dwordx4 v[192:195], v[224:225], off offset:576
	v_lshl_add_u64 v[224:225], s[34:35], 0, v[150:151]
	v_lshl_add_u64 v[224:225], v[224:225], 0, v[172:173]
	global_load_dwordx4 v[196:199], v[224:225], off
	global_load_dwordx4 v[200:203], v[224:225], off offset:64
	global_load_dwordx4 v[204:207], v[224:225], off offset:512
	global_load_dwordx4 v[208:211], v[224:225], off offset:576
	v_lshl_add_u64 v[226:227], s[34:35], 0, v[148:149]
	v_lshl_add_u64 v[226:227], v[226:227], 0, v[172:173]
	s_waitcnt vmcnt(7)
	v_pk_mul_f32 v[182:183], v[182:183], s[14:15] op_sel_hi:[1,0]
	v_pk_mul_f32 v[180:181], v[180:181], s[14:15] op_sel_hi:[1,0]
	v_pk_fma_f32 v[182:183], v[126:127], v[142:143], v[182:183]
	v_pk_fma_f32 v[180:181], v[124:125], v[140:141], v[180:181]
	global_store_dwordx4 v[226:227], v[180:183], off
	s_waitcnt vmcnt(7)
	v_pk_mul_f32 v[186:187], v[186:187], s[14:15] op_sel_hi:[1,0]
	v_pk_mul_f32 v[184:185], v[184:185], s[14:15] op_sel_hi:[1,0]
	v_pk_fma_f32 v[186:187], v[122:123], v[138:139], v[186:187]
	v_pk_fma_f32 v[184:185], v[120:121], v[136:137], v[184:185]
	global_store_dwordx4 v[226:227], v[184:187], off offset:64
	s_waitcnt vmcnt(7)
	v_pk_mul_f32 v[190:191], v[190:191], s[14:15] op_sel_hi:[1,0]
	v_pk_mul_f32 v[188:189], v[188:189], s[14:15] op_sel_hi:[1,0]
	v_pk_fma_f32 v[190:191], v[118:119], v[134:135], v[190:191]
	v_pk_fma_f32 v[188:189], v[116:117], v[132:133], v[188:189]
	global_store_dwordx4 v[226:227], v[188:191], off offset:512
	s_waitcnt vmcnt(7)
	v_pk_mul_f32 v[194:195], v[194:195], s[14:15] op_sel_hi:[1,0]
	v_pk_mul_f32 v[192:193], v[192:193], s[14:15] op_sel_hi:[1,0]
	v_pk_fma_f32 v[194:195], v[114:115], v[130:131], v[194:195]
	v_pk_fma_f32 v[192:193], v[112:113], v[128:129], v[192:193]
	global_store_dwordx4 v[226:227], v[192:195], off offset:576
	s_nop 1
	v_lshl_add_u64 v[226:227], s[34:35], 0, v[150:151]
	v_lshl_add_u64 v[226:227], v[226:227], 0, v[172:173]
	s_waitcnt vmcnt(7)
	v_pk_mul_f32 v[198:199], v[198:199], s[14:15] op_sel_hi:[1,0]
	v_pk_mul_f32 v[196:197], v[196:197], s[14:15] op_sel_hi:[1,0]
	v_pk_fma_f32 v[198:199], v[110:111], v[142:143], v[198:199]
	v_pk_fma_f32 v[196:197], v[108:109], v[140:141], v[196:197]
	global_store_dwordx4 v[226:227], v[196:199], off
	s_waitcnt vmcnt(7)
	v_pk_mul_f32 v[202:203], v[202:203], s[14:15] op_sel_hi:[1,0]
	v_pk_mul_f32 v[200:201], v[200:201], s[14:15] op_sel_hi:[1,0]
	v_pk_fma_f32 v[202:203], v[106:107], v[138:139], v[202:203]
	v_pk_fma_f32 v[200:201], v[104:105], v[136:137], v[200:201]
	global_store_dwordx4 v[226:227], v[200:203], off offset:64
	s_waitcnt vmcnt(7)
	v_pk_mul_f32 v[206:207], v[206:207], s[14:15] op_sel_hi:[1,0]
	v_pk_mul_f32 v[204:205], v[204:205], s[14:15] op_sel_hi:[1,0]
	v_pk_fma_f32 v[206:207], v[102:103], v[134:135], v[206:207]
	v_pk_fma_f32 v[204:205], v[100:101], v[132:133], v[204:205]
	global_store_dwordx4 v[226:227], v[204:207], off offset:512
	s_waitcnt vmcnt(7)
	v_pk_mul_f32 v[210:211], v[210:211], s[14:15] op_sel_hi:[1,0]
	v_pk_mul_f32 v[208:209], v[208:209], s[14:15] op_sel_hi:[1,0]
	v_pk_fma_f32 v[210:211], v[98:99], v[130:131], v[210:211]
	v_pk_fma_f32 v[208:209], v[96:97], v[128:129], v[208:209]
	global_store_dwordx4 v[226:227], v[208:211], off offset:576
	s_nop 1
	v_lshl_add_u64 v[224:225], s[34:35], 0, v[152:153]
	v_lshl_add_u64 v[224:225], v[224:225], 0, v[172:173]
	global_load_dwordx4 v[124:127], v[224:225], off
	global_load_dwordx4 v[120:123], v[224:225], off offset:64
	global_load_dwordx4 v[116:119], v[224:225], off offset:512
	global_load_dwordx4 v[112:115], v[224:225], off offset:576
	v_lshl_add_u64 v[224:225], s[34:35], 0, v[154:155]
	v_lshl_add_u64 v[224:225], v[224:225], 0, v[172:173]
	global_load_dwordx4 v[108:111], v[224:225], off
	global_load_dwordx4 v[104:107], v[224:225], off offset:64
	global_load_dwordx4 v[100:103], v[224:225], off offset:512
	global_load_dwordx4 v[96:99], v[224:225], off offset:576
	v_lshl_add_u64 v[224:225], s[34:35], 0, v[156:157]
	v_lshl_add_u64 v[224:225], v[224:225], 0, v[172:173]
	global_load_dwordx4 v[212:215], v[224:225], off
	global_load_dwordx4 v[216:219], v[224:225], off offset:64
	global_load_dwordx4 v[220:223], v[224:225], off offset:512
	global_load_dwordx4 v[180:183], v[224:225], off offset:576
	v_lshl_add_u64 v[226:227], s[34:35], 0, v[152:153]
	v_lshl_add_u64 v[226:227], v[226:227], 0, v[172:173]
	s_waitcnt vmcnt(11)
	v_pk_mul_f32 v[126:127], v[126:127], s[14:15] op_sel_hi:[1,0]
	v_pk_mul_f32 v[124:125], v[124:125], s[14:15] op_sel_hi:[1,0]
	v_pk_fma_f32 v[126:127], v[94:95], v[142:143], v[126:127]
	v_pk_fma_f32 v[124:125], v[92:93], v[140:141], v[124:125]
	global_store_dwordx4 v[226:227], v[124:127], off
	s_waitcnt vmcnt(11)
;     __device__ __forceinline__ void operator()(const pg8::f32x4 (&acc)[2][2][4][2], const pg8::Unit& u, int wr, int wc, int fr, int fq) const {
;     ...
;         for (int ai = 0; ai < 2; ++ai)
; #pragma unroll
;             for (int m = 0; m < 4; ++m) { const size_t off = (size_t)(wr * 64 + fr + ai * 128 + m * 16) * D + col0;
; #pragma unroll
;                 for (int bj = 0; bj < 2; ++bj)
; #pragma unroll
;                     for (int n = 0; n < 2; ++n) { const pg8::f32x4 s = *(const pg8::f32x4*)(src + off + bj * 128 + n * 16);
;                         *(pg8::f32x4*)(dst + off + bj * 128 + n * 16) = s * ALPHA + gv[bj][n] * acc[ai][bj][m][n]; }
;                 asm volatile("" ::: "memory"); }
	v_pk_mul_f32 v[122:123], v[122:123], s[14:15] op_sel_hi:[1,0]
	v_pk_mul_f32 v[120:121], v[120:121], s[14:15] op_sel_hi:[1,0]
	v_pk_fma_f32 v[122:123], v[90:91], v[138:139], v[122:123]
	v_pk_fma_f32 v[120:121], v[88:89], v[136:137], v[120:121]
	global_store_dwordx4 v[226:227], v[120:123], off offset:64
	s_waitcnt vmcnt(11)
	v_pk_mul_f32 v[118:119], v[118:119], s[14:15] op_sel_hi:[1,0]
	v_pk_mul_f32 v[116:117], v[116:117], s[14:15] op_sel_hi:[1,0]
	v_pk_fma_f32 v[118:119], v[86:87], v[134:135], v[118:119]
	v_pk_fma_f32 v[116:117], v[84:85], v[132:133], v[116:117]
	global_store_dwordx4 v[226:227], v[116:119], off offset:512
	s_waitcnt vmcnt(11)
	v_pk_mul_f32 v[114:115], v[114:115], s[14:15] op_sel_hi:[1,0]
	v_pk_mul_f32 v[112:113], v[112:113], s[14:15] op_sel_hi:[1,0]
	v_pk_fma_f32 v[114:115], v[82:83], v[130:131], v[114:115]
	v_pk_fma_f32 v[112:113], v[80:81], v[128:129], v[112:113]
	global_store_dwordx4 v[226:227], v[112:115], off offset:576
	s_nop 1
	v_lshl_add_u64 v[226:227], s[34:35], 0, v[154:155]
	v_lshl_add_u64 v[226:227], v[226:227], 0, v[172:173]
	s_waitcnt vmcnt(11)
	v_pk_mul_f32 v[110:111], v[110:111], s[14:15] op_sel_hi:[1,0]
	v_pk_mul_f32 v[108:109], v[108:109], s[14:15] op_sel_hi:[1,0]
	v_pk_fma_f32 v[110:111], v[78:79], v[142:143], v[110:111]
	v_pk_fma_f32 v[108:109], v[76:77], v[140:141], v[108:109]
	global_store_dwordx4 v[226:227], v[108:111], off
	s_waitcnt vmcnt(11)
	v_pk_mul_f32 v[106:107], v[106:107], s[14:15] op_sel_hi:[1,0]
	v_pk_mul_f32 v[104:105], v[104:105], s[14:15] op_sel_hi:[1,0]
	v_pk_fma_f32 v[106:107], v[74:75], v[138:139], v[106:107]
	v_pk_fma_f32 v[104:105], v[72:73], v[136:137], v[104:105]
	global_store_dwordx4 v[226:227], v[104:107], off offset:64
	s_waitcnt vmcnt(11)
	v_pk_mul_f32 v[102:103], v[102:103], s[14:15] op_sel_hi:[1,0]
	v_pk_mul_f32 v[100:101], v[100:101], s[14:15] op_sel_hi:[1,0]
	v_pk_fma_f32 v[102:103], v[70:71], v[134:135], v[102:103]
	v_pk_fma_f32 v[100:101], v[68:69], v[132:133], v[100:101]
	global_store_dwordx4 v[226:227], v[100:103], off offset:512
	s_waitcnt vmcnt(11)
	v_pk_mul_f32 v[98:99], v[98:99], s[14:15] op_sel_hi:[1,0]
	v_pk_mul_f32 v[96:97], v[96:97], s[14:15] op_sel_hi:[1,0]
	v_pk_fma_f32 v[98:99], v[66:67], v[130:131], v[98:99]
	v_pk_fma_f32 v[96:97], v[64:65], v[128:129], v[96:97]
	global_store_dwordx4 v[226:227], v[96:99], off offset:576
	s_nop 1
	v_lshl_add_u64 v[226:227], s[34:35], 0, v[156:157]
	v_lshl_add_u64 v[226:227], v[226:227], 0, v[172:173]
	s_waitcnt vmcnt(11)
	v_pk_mul_f32 v[214:215], v[214:215], s[14:15] op_sel_hi:[1,0]
	v_pk_mul_f32 v[212:213], v[212:213], s[14:15] op_sel_hi:[1,0]
	v_pk_fma_f32 v[214:215], v[62:63], v[142:143], v[214:215]
	v_pk_fma_f32 v[212:213], v[60:61], v[140:141], v[212:213]
	global_store_dwordx4 v[226:227], v[212:215], off
	s_waitcnt vmcnt(11)
	v_pk_mul_f32 v[218:219], v[218:219], s[14:15] op_sel_hi:[1,0]
	v_pk_mul_f32 v[216:217], v[216:217], s[14:15] op_sel_hi:[1,0]
	v_pk_fma_f32 v[218:219], v[58:59], v[138:139], v[218:219]
	v_pk_fma_f32 v[216:217], v[56:57], v[136:137], v[216:217]
	global_store_dwordx4 v[226:227], v[216:219], off offset:64
	s_waitcnt vmcnt(11)
	v_pk_mul_f32 v[222:223], v[222:223], s[14:15] op_sel_hi:[1,0]
	v_pk_mul_f32 v[220:221], v[220:221], s[14:15] op_sel_hi:[1,0]
	v_pk_fma_f32 v[222:223], v[54:55], v[134:135], v[222:223]
	v_pk_fma_f32 v[220:221], v[52:53], v[132:133], v[220:221]
	global_store_dwordx4 v[226:227], v[220:223], off offset:512
	s_waitcnt vmcnt(11)
	v_pk_mul_f32 v[182:183], v[182:183], s[14:15] op_sel_hi:[1,0]
	v_pk_mul_f32 v[180:181], v[180:181], s[14:15] op_sel_hi:[1,0]
	v_pk_fma_f32 v[182:183], v[50:51], v[130:131], v[182:183]
	v_pk_fma_f32 v[180:181], v[48:49], v[128:129], v[180:181]
	global_store_dwordx4 v[226:227], v[180:183], off offset:576
	s_nop 1
	v_lshl_add_u64 v[224:225], s[34:35], 0, v[158:159]
	v_lshl_add_u64 v[224:225], v[224:225], 0, v[172:173]
	global_load_dwordx4 v[184:187], v[224:225], off
	global_load_dwordx4 v[188:191], v[224:225], off offset:64
	global_load_dwordx4 v[192:195], v[224:225], off offset:512
	global_load_dwordx4 v[196:199], v[224:225], off offset:576
	v_lshl_add_u64 v[224:225], s[34:35], 0, v[160:161]
	v_lshl_add_u64 v[224:225], v[224:225], 0, v[172:173]
	global_load_dwordx4 v[200:203], v[224:225], off
	global_load_dwordx4 v[204:207], v[224:225], off offset:64
	global_load_dwordx4 v[208:211], v[224:225], off offset:512
	global_load_dwordx4 v[92:95], v[224:225], off offset:576
	v_lshl_add_u64 v[224:225], s[34:35], 0, v[162:163]
	v_lshl_add_u64 v[224:225], v[224:225], 0, v[172:173]
	global_load_dwordx4 v[88:91], v[224:225], off
	global_load_dwordx4 v[84:87], v[224:225], off offset:64
	global_load_dwordx4 v[80:83], v[224:225], off offset:512
	global_load_dwordx4 v[76:79], v[224:225], off offset:576
	v_lshl_add_u64 v[226:227], s[34:35], 0, v[158:159]
	v_lshl_add_u64 v[226:227], v[226:227], 0, v[172:173]
	s_waitcnt vmcnt(11)
; template <class Epi, class Sched, bool ALIGN_EPI = false, bool SP2 = false>
; __device__ __forceinline__ void gemm_phase(PG8_LAS unsigned char* lds, const Gemm g, const Sched& S, const Epi& E) {
;     ...
;         if constexpr (!Epi::AFTER_DRAIN) { E(acc, cur, wr, wc, fr, fq); S.done(cur); }
;     __device__ __forceinline__ void operator()(const pg8::f32x4 (&acc)[2][2][4][2], const pg8::Unit& u, int wr, int wc, int fr, int fq) const {
;     ...
;         for (int ai = 0; ai < 2; ++ai)
; #pragma unroll
;             for (int m = 0; m < 4; ++m) { const size_t off = (size_t)(wr * 64 + fr + ai * 128 + m * 16) * D + col0;
; #pragma unroll
;                 for (int bj = 0; bj < 2; ++bj)
; #pragma unroll
;                     for (int n = 0; n < 2; ++n) { const pg8::f32x4 s = *(const pg8::f32x4*)(src + off + bj * 128 + n * 16);
;                         *(pg8::f32x4*)(dst + off + bj * 128 + n * 16) = s * ALPHA + gv[bj][n] * acc[ai][bj][m][n]; }
;                 asm volatile("" ::: "memory"); }
	v_pk_mul_f32 v[186:187], v[186:187], s[14:15] op_sel_hi:[1,0]
	v_pk_mul_f32 v[184:185], v[184:185], s[14:15] op_sel_hi:[1,0]
	v_pk_fma_f32 v[186:187], v[46:47], v[142:143], v[186:187]
	v_pk_fma_f32 v[184:185], v[44:45], v[140:141], v[184:185]
	global_store_dwordx4 v[226:227], v[184:187], off
	s_waitcnt vmcnt(11)
	v_pk_mul_f32 v[190:191], v[190:191], s[14:15] op_sel_hi:[1,0]
	v_pk_mul_f32 v[188:189], v[188:189], s[14:15] op_sel_hi:[1,0]
	v_pk_fma_f32 v[190:191], v[42:43], v[138:139], v[190:191]
	v_pk_fma_f32 v[188:189], v[40:41], v[136:137], v[188:189]
	global_store_dwordx4 v[226:227], v[188:191], off offset:64
	s_waitcnt vmcnt(11)
	v_pk_mul_f32 v[194:195], v[194:195], s[14:15] op_sel_hi:[1,0]
	v_pk_mul_f32 v[192:193], v[192:193], s[14:15] op_sel_hi:[1,0]
	v_pk_fma_f32 v[194:195], v[38:39], v[134:135], v[194:195]
	v_pk_fma_f32 v[192:193], v[36:37], v[132:133], v[192:193]
	global_store_dwordx4 v[226:227], v[192:195], off offset:512
	s_waitcnt vmcnt(11)
	v_pk_mul_f32 v[198:199], v[198:199], s[14:15] op_sel_hi:[1,0]
	v_pk_mul_f32 v[196:197], v[196:197], s[14:15] op_sel_hi:[1,0]
	v_pk_fma_f32 v[198:199], v[34:35], v[130:131], v[198:199]
	v_pk_fma_f32 v[196:197], v[32:33], v[128:129], v[196:197]
	global_store_dwordx4 v[226:227], v[196:199], off offset:576
	s_nop 1
	v_lshl_add_u64 v[226:227], s[34:35], 0, v[160:161]
	v_lshl_add_u64 v[226:227], v[226:227], 0, v[172:173]
	s_waitcnt vmcnt(11)
	v_pk_mul_f32 v[202:203], v[202:203], s[14:15] op_sel_hi:[1,0]
	v_pk_mul_f32 v[200:201], v[200:201], s[14:15] op_sel_hi:[1,0]
	v_pk_fma_f32 v[202:203], v[30:31], v[142:143], v[202:203]
	v_pk_fma_f32 v[200:201], v[28:29], v[140:141], v[200:201]
	global_store_dwordx4 v[226:227], v[200:203], off
	s_waitcnt vmcnt(11)
	v_pk_mul_f32 v[206:207], v[206:207], s[14:15] op_sel_hi:[1,0]
	v_pk_mul_f32 v[204:205], v[204:205], s[14:15] op_sel_hi:[1,0]
	v_pk_fma_f32 v[206:207], v[26:27], v[138:139], v[206:207]
	v_pk_fma_f32 v[204:205], v[24:25], v[136:137], v[204:205]
	global_store_dwordx4 v[226:227], v[204:207], off offset:64
	s_waitcnt vmcnt(11)
	v_pk_mul_f32 v[210:211], v[210:211], s[14:15] op_sel_hi:[1,0]
	v_pk_mul_f32 v[208:209], v[208:209], s[14:15] op_sel_hi:[1,0]
	v_pk_fma_f32 v[210:211], v[22:23], v[134:135], v[210:211]
	v_pk_fma_f32 v[208:209], v[20:21], v[132:133], v[208:209]
	global_store_dwordx4 v[226:227], v[208:211], off offset:512
	s_waitcnt vmcnt(11)
	v_pk_mul_f32 v[94:95], v[94:95], s[14:15] op_sel_hi:[1,0]
	v_pk_mul_f32 v[92:93], v[92:93], s[14:15] op_sel_hi:[1,0]
	v_pk_fma_f32 v[94:95], v[18:19], v[130:131], v[94:95]
	v_pk_fma_f32 v[92:93], v[16:17], v[128:129], v[92:93]
	global_store_dwordx4 v[226:227], v[92:95], off offset:576
	s_nop 1
	v_lshl_add_u64 v[226:227], s[34:35], 0, v[162:163]
	v_lshl_add_u64 v[226:227], v[226:227], 0, v[172:173]
	s_waitcnt vmcnt(11)
	v_pk_mul_f32 v[90:91], v[90:91], s[14:15] op_sel_hi:[1,0]
	v_pk_mul_f32 v[88:89], v[88:89], s[14:15] op_sel_hi:[1,0]
	v_pk_fma_f32 v[90:91], v[14:15], v[142:143], v[90:91]
	v_pk_fma_f32 v[88:89], v[12:13], v[140:141], v[88:89]
	global_store_dwordx4 v[226:227], v[88:91], off
	s_waitcnt vmcnt(11)
	v_pk_mul_f32 v[86:87], v[86:87], s[14:15] op_sel_hi:[1,0]
	v_pk_mul_f32 v[84:85], v[84:85], s[14:15] op_sel_hi:[1,0]
	v_pk_fma_f32 v[86:87], v[10:11], v[138:139], v[86:87]
	v_pk_fma_f32 v[84:85], v[8:9], v[136:137], v[84:85]
	global_store_dwordx4 v[226:227], v[84:87], off offset:64
	s_waitcnt vmcnt(11)
	v_pk_mul_f32 v[82:83], v[82:83], s[14:15] op_sel_hi:[1,0]
	v_pk_mul_f32 v[80:81], v[80:81], s[14:15] op_sel_hi:[1,0]
	v_pk_fma_f32 v[82:83], v[6:7], v[134:135], v[82:83]
	v_pk_fma_f32 v[80:81], v[4:5], v[132:133], v[80:81]
	global_store_dwordx4 v[226:227], v[80:83], off offset:512
	s_waitcnt vmcnt(11)
	v_pk_mul_f32 v[78:79], v[78:79], s[14:15] op_sel_hi:[1,0]
	v_pk_mul_f32 v[76:77], v[76:77], s[14:15] op_sel_hi:[1,0]
	v_pk_fma_f32 v[78:79], v[2:3], v[130:131], v[78:79]
	v_pk_fma_f32 v[76:77], v[0:1], v[128:129], v[76:77]
	global_store_dwordx4 v[226:227], v[76:79], off offset:576
	s_nop 1
	s_cbranch_vccnz .LBB0_1757
	s_andn2_b64 vcc, exec, s[8:9]
	s_cbranch_vccnz .LBB0_1756
	s_barrier
	s_branch .LBB0_1756

;     __device__ __forceinline__ void operator()(const pg8::f32x4 (&acc)[2][2][4][2], const pg8::Unit& u, int wr, int wc, int fr, int fq) const {
;         const int R0 = u.pm * 256; const float* src; float* dst; int mv;
;         if (R0 < ML) { src = srcL + (size_t)R0 * D; dst = dstL + (size_t)R0 * D; mv = (R0 >= SEQ) ? 1 : 0; }
;         else { src = srcC + (size_t)(R0 - ML) * D; dst = dstC + (size_t)(R0 - ML) * D; mv = 2; }
;         const int col0 = u.pn * 256 + wc * 32 + 4 * fq; const float* gt = gate + mv * NMOD + col0;
;         pg8::f32x4 gv[2][2];
; #pragma unroll
;         for (int bj = 0; bj < 2; ++bj)
; #pragma unroll
;             for (int n = 0; n < 2; ++n) gv[bj][n] = *(const pg8::f32x4*)(gt + bj * 128 + n * 16);
; #pragma unroll
;         for (int ai = 0; ai < 2; ++ai)
; #pragma unroll
;             for (int m = 0; m < 4; ++m) { const size_t off = (size_t)(wr * 64 + fr + ai * 128 + m * 16) * D + col0;
; #pragma unroll
;                 for (int bj = 0; bj < 2; ++bj)
; #pragma unroll
;                     for (int n = 0; n < 2; ++n) { const pg8::f32x4 s = *(const pg8::f32x4*)(src + off + bj * 128 + n * 16);
;                         *(pg8::f32x4*)(dst + off + bj * 128 + n * 16) = s * ALPHA + gv[bj][n] * acc[ai][bj][m][n]; }
;                 asm volatile("" ::: "memory"); }
.LBB0_1994:
	v_lshl_or_b32 v128, s49, 8, v176
	v_ashrrev_i32_e32 v129, 31, v128
	v_lshlrev_b64 v[172:173], 2, v[128:129]
	s_lshl_b32 s2, s34, 2
	s_add_u32 s30, s40, s2
	s_addc_u32 s31, s41, 0
	v_lshl_add_u64 v[128:129], s[30:31], 0, v[172:173]
	global_load_dwordx4 v[140:143], v[128:129], off
	global_load_dwordx4 v[136:139], v[128:129], off offset:64
	global_load_dwordx4 v[132:135], v[128:129], off offset:512
	s_nop 0
	global_load_dwordx4 v[128:131], v[128:129], off offset:576
	s_andn2_b64 vcc, exec, s[0:1]
	s_mov_b64 s[0:1], -1
	v_lshl_add_u64 v[224:225], s[26:27], 0, v[148:149]
	v_lshl_add_u64 v[224:225], v[224:225], 0, v[172:173]
	global_load_dwordx4 v[180:183], v[224:225], off
	global_load_dwordx4 v[184:187], v[224:225], off offset:64
	global_load_dwordx4 v[188:191], v[224:225], off offset:512
	global_load_dwordx4 v[192:195], v[224:225], off offset:576
	v_lshl_add_u64 v[224:225], s[26:27], 0, v[150:151]
	v_lshl_add_u64 v[224:225], v[224:225], 0, v[172:173]
	global_load_dwordx4 v[196:199], v[224:225], off
	global_load_dwordx4 v[200:203], v[224:225], off offset:64
	global_load_dwordx4 v[204:207], v[224:225], off offset:512
	global_load_dwordx4 v[208:211], v[224:225], off offset:576
	v_lshl_add_u64 v[226:227], s[26:27], 0, v[148:149]
	v_lshl_add_u64 v[226:227], v[226:227], 0, v[172:173]
	s_waitcnt vmcnt(7)
	v_pk_mul_f32 v[182:183], v[182:183], s[14:15] op_sel_hi:[1,0]
	v_pk_mul_f32 v[180:181], v[180:181], s[14:15] op_sel_hi:[1,0]
	v_pk_fma_f32 v[182:183], v[126:127], v[142:143], v[182:183]
	v_pk_fma_f32 v[180:181], v[124:125], v[140:141], v[180:181]
	global_store_dwordx4 v[226:227], v[180:183], off
	s_waitcnt vmcnt(7)
	v_pk_mul_f32 v[186:187], v[186:187], s[14:15] op_sel_hi:[1,0]
	v_pk_mul_f32 v[184:185], v[184:185], s[14:15] op_sel_hi:[1,0]
	v_pk_fma_f32 v[186:187], v[122:123], v[138:139], v[186:187]
	v_pk_fma_f32 v[184:185], v[120:121], v[136:137], v[184:185]
	global_store_dwordx4 v[226:227], v[184:187], off offset:64
	s_waitcnt vmcnt(7)
	v_pk_mul_f32 v[190:191], v[190:191], s[14:15] op_sel_hi:[1,0]
	v_pk_mul_f32 v[188:189], v[188:189], s[14:15] op_sel_hi:[1,0]
	v_pk_fma_f32 v[190:191], v[118:119], v[134:135], v[190:191]
	v_pk_fma_f32 v[188:189], v[116:117], v[132:133], v[188:189]
	global_store_dwordx4 v[226:227], v[188:191], off offset:512
	s_waitcnt vmcnt(7)
	v_pk_mul_f32 v[194:195], v[194:195], s[14:15] op_sel_hi:[1,0]
	v_pk_mul_f32 v[192:193], v[192:193], s[14:15] op_sel_hi:[1,0]
	v_pk_fma_f32 v[194:195], v[114:115], v[130:131], v[194:195]
	v_pk_fma_f32 v[192:193], v[112:113], v[128:129], v[192:193]
	global_store_dwordx4 v[226:227], v[192:195], off offset:576
	s_nop 1
	v_lshl_add_u64 v[226:227], s[26:27], 0, v[150:151]
	v_lshl_add_u64 v[226:227], v[226:227], 0, v[172:173]
	s_waitcnt vmcnt(7)
	v_pk_mul_f32 v[198:199], v[198:199], s[14:15] op_sel_hi:[1,0]
	v_pk_mul_f32 v[196:197], v[196:197], s[14:15] op_sel_hi:[1,0]
	v_pk_fma_f32 v[198:199], v[110:111], v[142:143], v[198:199]
	v_pk_fma_f32 v[196:197], v[108:109], v[140:141], v[196:197]
	global_store_dwordx4 v[226:227], v[196:199], off
	s_waitcnt vmcnt(7)
	v_pk_mul_f32 v[202:203], v[202:203], s[14:15] op_sel_hi:[1,0]
	v_pk_mul_f32 v[200:201], v[200:201], s[14:15] op_sel_hi:[1,0]
	v_pk_fma_f32 v[202:203], v[106:107], v[138:139], v[202:203]
	v_pk_fma_f32 v[200:201], v[104:105], v[136:137], v[200:201]
	global_store_dwordx4 v[226:227], v[200:203], off offset:64
	s_waitcnt vmcnt(7)
	v_pk_mul_f32 v[206:207], v[206:207], s[14:15] op_sel_hi:[1,0]
	v_pk_mul_f32 v[204:205], v[204:205], s[14:15] op_sel_hi:[1,0]
	v_pk_fma_f32 v[206:207], v[102:103], v[134:135], v[206:207]
	v_pk_fma_f32 v[204:205], v[100:101], v[132:133], v[204:205]
	global_store_dwordx4 v[226:227], v[204:207], off offset:512
	s_waitcnt vmcnt(7)
	v_pk_mul_f32 v[210:211], v[210:211], s[14:15] op_sel_hi:[1,0]
	v_pk_mul_f32 v[208:209], v[208:209], s[14:15] op_sel_hi:[1,0]
	v_pk_fma_f32 v[210:211], v[98:99], v[130:131], v[210:211]
	v_pk_fma_f32 v[208:209], v[96:97], v[128:129], v[208:209]
	global_store_dwordx4 v[226:227], v[208:211], off offset:576
	s_nop 1
	v_lshl_add_u64 v[224:225], s[26:27], 0, v[152:153]
	v_lshl_add_u64 v[224:225], v[224:225], 0, v[172:173]
	global_load_dwordx4 v[124:127], v[224:225], off
	global_load_dwordx4 v[120:123], v[224:225], off offset:64
	global_load_dwordx4 v[116:119], v[224:225], off offset:512
	global_load_dwordx4 v[112:115], v[224:225], off offset:576
	v_lshl_add_u64 v[224:225], s[26:27], 0, v[154:155]
	v_lshl_add_u64 v[224:225], v[224:225], 0, v[172:173]
	global_load_dwordx4 v[108:111], v[224:225], off
	global_load_dwordx4 v[104:107], v[224:225], off offset:64
	global_load_dwordx4 v[100:103], v[224:225], off offset:512
	global_load_dwordx4 v[96:99], v[224:225], off offset:576
	v_lshl_add_u64 v[224:225], s[26:27], 0, v[156:157]
	v_lshl_add_u64 v[224:225], v[224:225], 0, v[172:173]
	global_load_dwordx4 v[212:215], v[224:225], off
	global_load_dwordx4 v[216:219], v[224:225], off offset:64
	global_load_dwordx4 v[220:223], v[224:225], off offset:512
	global_load_dwordx4 v[180:183], v[224:225], off offset:576
	v_lshl_add_u64 v[226:227], s[26:27], 0, v[152:153]
	v_lshl_add_u64 v[226:227], v[226:227], 0, v[172:173]
	s_waitcnt vmcnt(11)
	v_pk_mul_f32 v[126:127], v[126:127], s[14:15] op_sel_hi:[1,0]
	v_pk_mul_f32 v[124:125], v[124:125], s[14:15] op_sel_hi:[1,0]
	v_pk_fma_f32 v[126:127], v[94:95], v[142:143], v[126:127]
	v_pk_fma_f32 v[124:125], v[92:93], v[140:141], v[124:125]
	global_store_dwordx4 v[226:227], v[124:127], off
	s_waitcnt vmcnt(11)
;     __device__ __forceinline__ void operator()(const pg8::f32x4 (&acc)[2][2][4][2], const pg8::Unit& u, int wr, int wc, int fr, int fq) const {
;     ...
;         for (int ai = 0; ai < 2; ++ai)
; #pragma unroll
;             for (int m = 0; m < 4; ++m) { const size_t off = (size_t)(wr * 64 + fr + ai * 128 + m * 16) * D + col0;
; #pragma unroll
;                 for (int bj = 0; bj < 2; ++bj)
; #pragma unroll
;                     for (int n = 0; n < 2; ++n) { const pg8::f32x4 s = *(const pg8::f32x4*)(src + off + bj * 128 + n * 16);
;                         *(pg8::f32x4*)(dst + off + bj * 128 + n * 16) = s * ALPHA + gv[bj][n] * acc[ai][bj][m][n]; }
;                 asm volatile("" ::: "memory"); }
	v_pk_mul_f32 v[122:123], v[122:123], s[14:15] op_sel_hi:[1,0]
	v_pk_mul_f32 v[120:121], v[120:121], s[14:15] op_sel_hi:[1,0]
	v_pk_fma_f32 v[122:123], v[90:91], v[138:139], v[122:123]
	v_pk_fma_f32 v[120:121], v[88:89], v[136:137], v[120:121]
	global_store_dwordx4 v[226:227], v[120:123], off offset:64
	s_waitcnt vmcnt(11)
	v_pk_mul_f32 v[118:119], v[118:119], s[14:15] op_sel_hi:[1,0]
	v_pk_mul_f32 v[116:117], v[116:117], s[14:15] op_sel_hi:[1,0]
	v_pk_fma_f32 v[118:119], v[86:87], v[134:135], v[118:119]
	v_pk_fma_f32 v[116:117], v[84:85], v[132:133], v[116:117]
	global_store_dwordx4 v[226:227], v[116:119], off offset:512
	s_waitcnt vmcnt(11)
	v_pk_mul_f32 v[114:115], v[114:115], s[14:15] op_sel_hi:[1,0]
	v_pk_mul_f32 v[112:113], v[112:113], s[14:15] op_sel_hi:[1,0]
	v_pk_fma_f32 v[114:115], v[82:83], v[130:131], v[114:115]
	v_pk_fma_f32 v[112:113], v[80:81], v[128:129], v[112:113]
	global_store_dwordx4 v[226:227], v[112:115], off offset:576
	s_nop 1
	v_lshl_add_u64 v[226:227], s[26:27], 0, v[154:155]
	v_lshl_add_u64 v[226:227], v[226:227], 0, v[172:173]
	s_waitcnt vmcnt(11)
	v_pk_mul_f32 v[110:111], v[110:111], s[14:15] op_sel_hi:[1,0]
	v_pk_mul_f32 v[108:109], v[108:109], s[14:15] op_sel_hi:[1,0]
	v_pk_fma_f32 v[110:111], v[78:79], v[142:143], v[110:111]
	v_pk_fma_f32 v[108:109], v[76:77], v[140:141], v[108:109]
	global_store_dwordx4 v[226:227], v[108:111], off
	s_waitcnt vmcnt(11)
	v_pk_mul_f32 v[106:107], v[106:107], s[14:15] op_sel_hi:[1,0]
	v_pk_mul_f32 v[104:105], v[104:105], s[14:15] op_sel_hi:[1,0]
	v_pk_fma_f32 v[106:107], v[74:75], v[138:139], v[106:107]
	v_pk_fma_f32 v[104:105], v[72:73], v[136:137], v[104:105]
	global_store_dwordx4 v[226:227], v[104:107], off offset:64
	s_waitcnt vmcnt(11)
	v_pk_mul_f32 v[102:103], v[102:103], s[14:15] op_sel_hi:[1,0]
	v_pk_mul_f32 v[100:101], v[100:101], s[14:15] op_sel_hi:[1,0]
	v_pk_fma_f32 v[102:103], v[70:71], v[134:135], v[102:103]
	v_pk_fma_f32 v[100:101], v[68:69], v[132:133], v[100:101]
	global_store_dwordx4 v[226:227], v[100:103], off offset:512
	s_waitcnt vmcnt(11)
	v_pk_mul_f32 v[98:99], v[98:99], s[14:15] op_sel_hi:[1,0]
	v_pk_mul_f32 v[96:97], v[96:97], s[14:15] op_sel_hi:[1,0]
	v_pk_fma_f32 v[98:99], v[66:67], v[130:131], v[98:99]
	v_pk_fma_f32 v[96:97], v[64:65], v[128:129], v[96:97]
	global_store_dwordx4 v[226:227], v[96:99], off offset:576
	s_nop 1
	v_lshl_add_u64 v[226:227], s[26:27], 0, v[156:157]
	v_lshl_add_u64 v[226:227], v[226:227], 0, v[172:173]
	s_waitcnt vmcnt(11)
	v_pk_mul_f32 v[214:215], v[214:215], s[14:15] op_sel_hi:[1,0]
	v_pk_mul_f32 v[212:213], v[212:213], s[14:15] op_sel_hi:[1,0]
	v_pk_fma_f32 v[214:215], v[62:63], v[142:143], v[214:215]
	v_pk_fma_f32 v[212:213], v[60:61], v[140:141], v[212:213]
	global_store_dwordx4 v[226:227], v[212:215], off
	s_waitcnt vmcnt(11)
	v_pk_mul_f32 v[218:219], v[218:219], s[14:15] op_sel_hi:[1,0]
	v_pk_mul_f32 v[216:217], v[216:217], s[14:15] op_sel_hi:[1,0]
	v_pk_fma_f32 v[218:219], v[58:59], v[138:139], v[218:219]
	v_pk_fma_f32 v[216:217], v[56:57], v[136:137], v[216:217]
	global_store_dwordx4 v[226:227], v[216:219], off offset:64
	s_waitcnt vmcnt(11)
	v_pk_mul_f32 v[222:223], v[222:223], s[14:15] op_sel_hi:[1,0]
	v_pk_mul_f32 v[220:221], v[220:221], s[14:15] op_sel_hi:[1,0]
	v_pk_fma_f32 v[222:223], v[54:55], v[134:135], v[222:223]
	v_pk_fma_f32 v[220:221], v[52:53], v[132:133], v[220:221]
	global_store_dwordx4 v[226:227], v[220:223], off offset:512
	s_waitcnt vmcnt(11)
	v_pk_mul_f32 v[182:183], v[182:183], s[14:15] op_sel_hi:[1,0]
	v_pk_mul_f32 v[180:181], v[180:181], s[14:15] op_sel_hi:[1,0]
	v_pk_fma_f32 v[182:183], v[50:51], v[130:131], v[182:183]
	v_pk_fma_f32 v[180:181], v[48:49], v[128:129], v[180:181]
	global_store_dwordx4 v[226:227], v[180:183], off offset:576
	s_nop 1
	v_lshl_add_u64 v[224:225], s[26:27], 0, v[158:159]
	v_lshl_add_u64 v[224:225], v[224:225], 0, v[172:173]
	global_load_dwordx4 v[184:187], v[224:225], off
	global_load_dwordx4 v[188:191], v[224:225], off offset:64
	global_load_dwordx4 v[192:195], v[224:225], off offset:512
	global_load_dwordx4 v[196:199], v[224:225], off offset:576
	v_lshl_add_u64 v[224:225], s[26:27], 0, v[160:161]
	v_lshl_add_u64 v[224:225], v[224:225], 0, v[172:173]
	global_load_dwordx4 v[200:203], v[224:225], off
	global_load_dwordx4 v[204:207], v[224:225], off offset:64
	global_load_dwordx4 v[208:211], v[224:225], off offset:512
	global_load_dwordx4 v[92:95], v[224:225], off offset:576
	v_lshl_add_u64 v[224:225], s[26:27], 0, v[162:163]
	v_lshl_add_u64 v[224:225], v[224:225], 0, v[172:173]
	global_load_dwordx4 v[88:91], v[224:225], off
	global_load_dwordx4 v[84:87], v[224:225], off offset:64
	global_load_dwordx4 v[80:83], v[224:225], off offset:512
	global_load_dwordx4 v[76:79], v[224:225], off offset:576
	v_lshl_add_u64 v[226:227], s[26:27], 0, v[158:159]
	v_lshl_add_u64 v[226:227], v[226:227], 0, v[172:173]
	s_waitcnt vmcnt(11)
; template <class Epi, class Sched, bool ALIGN_EPI = false, bool SP2 = false>
; __device__ __forceinline__ void gemm_phase(PG8_LAS unsigned char* lds, const Gemm g, const Sched& S, const Epi& E) {
;     ...
;         if constexpr (!Epi::AFTER_DRAIN) { E(acc, cur, wr, wc, fr, fq); S.done(cur); }
;     __device__ __forceinline__ void operator()(const pg8::f32x4 (&acc)[2][2][4][2], const pg8::Unit& u, int wr, int wc, int fr, int fq) const {
;     ...
;         for (int ai = 0; ai < 2; ++ai)
; #pragma unroll
;             for (int m = 0; m < 4; ++m) { const size_t off = (size_t)(wr * 64 + fr + ai * 128 + m * 16) * D + col0;
; #pragma unroll
;                 for (int bj = 0; bj < 2; ++bj)
; #pragma unroll
;                     for (int n = 0; n < 2; ++n) { const pg8::f32x4 s = *(const pg8::f32x4*)(src + off + bj * 128 + n * 16);
;                         *(pg8::f32x4*)(dst + off + bj * 128 + n * 16) = s * ALPHA + gv[bj][n] * acc[ai][bj][m][n]; }
;                 asm volatile("" ::: "memory"); }
	v_pk_mul_f32 v[186:187], v[186:187], s[14:15] op_sel_hi:[1,0]
	v_pk_mul_f32 v[184:185], v[184:185], s[14:15] op_sel_hi:[1,0]
	v_pk_fma_f32 v[186:187], v[46:47], v[142:143], v[186:187]
	v_pk_fma_f32 v[184:185], v[44:45], v[140:141], v[184:185]
	global_store_dwordx4 v[226:227], v[184:187], off
	s_waitcnt vmcnt(11)
	v_pk_mul_f32 v[190:191], v[190:191], s[14:15] op_sel_hi:[1,0]
	v_pk_mul_f32 v[188:189], v[188:189], s[14:15] op_sel_hi:[1,0]
	v_pk_fma_f32 v[190:191], v[42:43], v[138:139], v[190:191]
	v_pk_fma_f32 v[188:189], v[40:41], v[136:137], v[188:189]
	global_store_dwordx4 v[226:227], v[188:191], off offset:64
	s_waitcnt vmcnt(11)
	v_pk_mul_f32 v[194:195], v[194:195], s[14:15] op_sel_hi:[1,0]
	v_pk_mul_f32 v[192:193], v[192:193], s[14:15] op_sel_hi:[1,0]
	v_pk_fma_f32 v[194:195], v[38:39], v[134:135], v[194:195]
	v_pk_fma_f32 v[192:193], v[36:37], v[132:133], v[192:193]
	global_store_dwordx4 v[226:227], v[192:195], off offset:512
	s_waitcnt vmcnt(11)
	v_pk_mul_f32 v[198:199], v[198:199], s[14:15] op_sel_hi:[1,0]
	v_pk_mul_f32 v[196:197], v[196:197], s[14:15] op_sel_hi:[1,0]
	v_pk_fma_f32 v[198:199], v[34:35], v[130:131], v[198:199]
	v_pk_fma_f32 v[196:197], v[32:33], v[128:129], v[196:197]
	global_store_dwordx4 v[226:227], v[196:199], off offset:576
	s_nop 1
	v_lshl_add_u64 v[226:227], s[26:27], 0, v[160:161]
	v_lshl_add_u64 v[226:227], v[226:227], 0, v[172:173]
	s_waitcnt vmcnt(11)
	v_pk_mul_f32 v[202:203], v[202:203], s[14:15] op_sel_hi:[1,0]
	v_pk_mul_f32 v[200:201], v[200:201], s[14:15] op_sel_hi:[1,0]
	v_pk_fma_f32 v[202:203], v[30:31], v[142:143], v[202:203]
	v_pk_fma_f32 v[200:201], v[28:29], v[140:141], v[200:201]
	global_store_dwordx4 v[226:227], v[200:203], off
	s_waitcnt vmcnt(11)
	v_pk_mul_f32 v[206:207], v[206:207], s[14:15] op_sel_hi:[1,0]
	v_pk_mul_f32 v[204:205], v[204:205], s[14:15] op_sel_hi:[1,0]
	v_pk_fma_f32 v[206:207], v[26:27], v[138:139], v[206:207]
	v_pk_fma_f32 v[204:205], v[24:25], v[136:137], v[204:205]
	global_store_dwordx4 v[226:227], v[204:207], off offset:64
	s_waitcnt vmcnt(11)
	v_pk_mul_f32 v[210:211], v[210:211], s[14:15] op_sel_hi:[1,0]
	v_pk_mul_f32 v[208:209], v[208:209], s[14:15] op_sel_hi:[1,0]
	v_pk_fma_f32 v[210:211], v[22:23], v[134:135], v[210:211]
	v_pk_fma_f32 v[208:209], v[20:21], v[132:133], v[208:209]
	global_store_dwordx4 v[226:227], v[208:211], off offset:512
	s_waitcnt vmcnt(11)
	v_pk_mul_f32 v[94:95], v[94:95], s[14:15] op_sel_hi:[1,0]
	v_pk_mul_f32 v[92:93], v[92:93], s[14:15] op_sel_hi:[1,0]
	v_pk_fma_f32 v[94:95], v[18:19], v[130:131], v[94:95]
	v_pk_fma_f32 v[92:93], v[16:17], v[128:129], v[92:93]
	global_store_dwordx4 v[226:227], v[92:95], off offset:576
	s_nop 1
	v_lshl_add_u64 v[226:227], s[26:27], 0, v[162:163]
	v_lshl_add_u64 v[226:227], v[226:227], 0, v[172:173]
	s_waitcnt vmcnt(11)
	v_pk_mul_f32 v[90:91], v[90:91], s[14:15] op_sel_hi:[1,0]
	v_pk_mul_f32 v[88:89], v[88:89], s[14:15] op_sel_hi:[1,0]
	v_pk_fma_f32 v[90:91], v[14:15], v[142:143], v[90:91]
	v_pk_fma_f32 v[88:89], v[12:13], v[140:141], v[88:89]
	global_store_dwordx4 v[226:227], v[88:91], off
	s_waitcnt vmcnt(11)
	v_pk_mul_f32 v[86:87], v[86:87], s[14:15] op_sel_hi:[1,0]
	v_pk_mul_f32 v[84:85], v[84:85], s[14:15] op_sel_hi:[1,0]
	v_pk_fma_f32 v[86:87], v[10:11], v[138:139], v[86:87]
	v_pk_fma_f32 v[84:85], v[8:9], v[136:137], v[84:85]
	global_store_dwordx4 v[226:227], v[84:87], off offset:64
	s_waitcnt vmcnt(11)
	v_pk_mul_f32 v[82:83], v[82:83], s[14:15] op_sel_hi:[1,0]
	v_pk_mul_f32 v[80:81], v[80:81], s[14:15] op_sel_hi:[1,0]
	v_pk_fma_f32 v[82:83], v[6:7], v[134:135], v[82:83]
	v_pk_fma_f32 v[80:81], v[4:5], v[132:133], v[80:81]
	global_store_dwordx4 v[226:227], v[80:83], off offset:512
	s_waitcnt vmcnt(11)
	v_pk_mul_f32 v[78:79], v[78:79], s[14:15] op_sel_hi:[1,0]
	v_pk_mul_f32 v[76:77], v[76:77], s[14:15] op_sel_hi:[1,0]
	v_pk_fma_f32 v[78:79], v[2:3], v[130:131], v[78:79]
	v_pk_fma_f32 v[76:77], v[0:1], v[128:129], v[76:77]
	global_store_dwordx4 v[226:227], v[76:79], off offset:576
	s_nop 1
	s_cbranch_vccnz .LBB0_1979
	s_andn2_b64 vcc, exec, s[8:9]
	s_cbranch_vccnz .LBB0_1978
	s_barrier
	s_branch .LBB0_1978
